# comb6 + in-proj and merge K-loops: early wave group loop copy with vmcnt(8) deferred to end of MFMA block
# baseline (speedup 1.0000x reference)
; #define PG8_STAGE(bufoff, gbase, voff) do { _Pragma("unroll") for (int _i = 0; _i < 2; ++_i) \
;         __builtin_amdgcn_global_load_lds((const unsigned*)((const char*)(gbase) + (voff)[_i]), (LAS unsigned*)(lds + (bufoff) + ldsw + _i * 8192), 16, 0, 0); } while (0)
; #define PG8_LDA(dst, b, h) do { _Pragma("unroll") for (int m = 0; m < 4; ++m) _Pragma("unroll") for (int k = 0; k < 2; ++k) dst[m][k] = *(const LAS bf16x8*)(lds + PG8_SA(b, h) + aoff + m * 2048 + k * 1024); } while (0)
; #define PG8_LDB(dst, b, h) do { _Pragma("unroll") for (int n = 0; n < 2; ++n) _Pragma("unroll") for (int k = 0; k < 2; ++k) dst[n][k] = *(const LAS bf16x8*)(lds + PG8_SB(b, h) + boff + n * 2048 + k * 1024); } while (0)
; #define PG8_MMA(ai, bj, At, Bt) do { __builtin_amdgcn_s_setprio(1); _Pragma("unroll") for (int m = 0; m < 4; ++m) _Pragma("unroll") for (int n = 0; n < 2; ++n) _Pragma("unroll") for (int k = 0; k < 2; ++k) \
;         acc[ai][bj][m][n] = __builtin_amdgcn_mfma_f32_16x16x32_bf16(Bt[n][k], At[m][k], acc[ai][bj][m][n], 0, 0, 0); __builtin_amdgcn_s_setprio(0); } while (0)
; #define PG8_BAR __builtin_amdgcn_s_barrier()
; template <class Epi, class Sched, bool ALIGN_EPI, class Hook = NoHook>
; __device__ __forceinline__ void gemm_phase(LAS unsigned char* lds, const Gemm g, const Sched& S, const Epi& E, const Hook& H = Hook()) {
;     ...
;         for (int tb = 0; tb < nt; tb += (Hook::ON ? Hook::SEG : nt)) {
;         const int te = Hook::ON ? tb + Hook::SEG : nt;
;         for (int t = tb; t < te; t += 2) {
;             const bool last = (t == nt - 2);
;             const char* a1 = cA + (size_t)(t + 1) * kstep;
;             const char* a2 = last ? nA : cA + (size_t)(t + 2) * kstep; const char* b2 = last ? nB : cB + (size_t)(t + 2) * kstep;
;             const char* a3 = a2 + kstep; const char* b3 = b2 + kstep;
;             if (last && has_next) S.a_ready(nxt);
;             PG8_LDB(B0, 0, 0); PG8_LDB(B1, 0, 1); PG8_SCHED; PG8_LDA(At, 0, 0); PG8_STAGE(PG8_SA(1, 1), a1 + hA, voffA);
;             PG8_WAIT_V(8); PG8_WAIT_L(0); PG8_BAR; PG8_MMA(0, 0, At, B0); PG8_MMA(0, 1, At, B1); PG8_BAR; PG8_SCHED;
;             PG8_LDA(At, 0, 1); PG8_STAGE(PG8_SB(0, 0), b2, voffB); PG8_STAGE(PG8_SB(0, 1), b2 + hB, voffB); PG8_STAGE(PG8_SA(0, 0), a2, voffA);
;             PG8_WAIT_V(8); PG8_WAIT_L(0); PG8_BAR; PG8_MMA(1, 0, At, B0); PG8_MMA(1, 1, At, B1); PG8_BAR; PG8_SCHED;
.LBB0_782:
	s_add_i32 s66, s65, 16
	s_mov_b64 s[26:27], s[24:25]
	s_mov_b32 s67, s65
	s_cmp_lg_u64 s[16:17], 0
	s_cbranch_scc0 .Lmy_d783B
.LBB0_783:
	v_add_u32_e32 v3, s56, v222
	s_add_i32 s67, s67, 2
	ds_read_b128 v[126:129], v3
	ds_read_b128 v[130:133], v3 offset:1024
	ds_read_b128 v[142:145], v3 offset:2048
	ds_read_b128 v[146:149], v3 offset:3072
	v_add_u32_e32 v3, s57, v222
	s_add_u32 s28, s22, s26
	s_addc_u32 s29, s23, s27
	s_add_u32 s28, s28, 0x100
	s_addc_u32 s29, s29, 0
	s_add_u32 s68, s63, s26
	s_addc_u32 s69, s64, s27
	s_cmpk_eq_i32 s26, 0x5f00
	s_cselect_b32 s31, s5, s29
	s_cselect_b32 s30, s4, s28
	s_cselect_b32 s29, s21, s69
	s_cselect_b32 s28, s20, s68
	ds_read_b128 v[150:153], v3
	ds_read_b128 v[154:157], v3 offset:1024
	ds_read_b128 v[158:161], v3 offset:2048
	ds_read_b128 v[162:165], v3 offset:3072
	v_lshl_add_u64 v[4:5], v[182:183], 0, s[26:27]
	s_add_i32 m0, s37, 0xc000
	s_nop 0
	global_load_lds_dwordx4 v[4:5], off
	ds_read_b128 v[186:189], v224
	ds_read_b128 v[190:193], v224 offset:1024
	ds_read_b128 v[194:197], v224 offset:2048
	ds_read_b128 v[198:201], v224 offset:3072
	ds_read_b128 v[202:205], v224 offset:4096
	ds_read_b128 v[206:209], v224 offset:5120
	ds_read_b128 v[210:213], v224 offset:6144
	ds_read_b128 v[214:217], v224 offset:7168
	v_lshl_add_u64 v[4:5], v[184:185], 0, s[26:27]
	s_add_i32 m0, s37, 0xe000
	s_nop 0
	global_load_lds_dwordx4 v[4:5], off
	s_waitcnt lgkmcnt(0)
	s_barrier
	s_setprio 1
	s_waitcnt lgkmcnt(0)
	v_mfma_f32_16x16x32_bf16 v[138:141], v[126:129], v[186:189], v[138:141]
	v_mfma_f32_16x16x32_bf16 v[134:137], v[142:145], v[186:189], v[134:137]
	v_mfma_f32_16x16x32_bf16 v[122:125], v[126:129], v[194:197], v[122:125]
	v_mfma_f32_16x16x32_bf16 v[118:121], v[142:145], v[194:197], v[118:121]
	v_mfma_f32_16x16x32_bf16 v[114:117], v[126:129], v[202:205], v[114:117]
	v_mfma_f32_16x16x32_bf16 v[110:113], v[142:145], v[202:205], v[110:113]
	v_mfma_f32_16x16x32_bf16 v[106:109], v[126:129], v[210:213], v[106:109]
	v_mfma_f32_16x16x32_bf16 v[102:105], v[142:145], v[210:213], v[102:105]
	v_mfma_f32_16x16x32_bf16 v[138:141], v[130:133], v[190:193], v[138:141]
	v_mfma_f32_16x16x32_bf16 v[134:137], v[146:149], v[190:193], v[134:137]
	v_mfma_f32_16x16x32_bf16 v[122:125], v[130:133], v[198:201], v[122:125]
	v_mfma_f32_16x16x32_bf16 v[118:121], v[146:149], v[198:201], v[118:121]
	v_mfma_f32_16x16x32_bf16 v[114:117], v[130:133], v[206:209], v[114:117]
	v_mfma_f32_16x16x32_bf16 v[110:113], v[146:149], v[206:209], v[110:113]
	v_mfma_f32_16x16x32_bf16 v[106:109], v[130:133], v[214:217], v[106:109]
	v_mfma_f32_16x16x32_bf16 v[102:105], v[146:149], v[214:217], v[102:105]
	s_setprio 0
	s_setprio 1
	v_mfma_f32_16x16x32_bf16 v[66:69], v[150:153], v[186:189], v[66:69]
	v_mfma_f32_16x16x32_bf16 v[62:65], v[158:161], v[186:189], v[62:65]
	v_mfma_f32_16x16x32_bf16 v[58:61], v[150:153], v[194:197], v[58:61]
	v_mfma_f32_16x16x32_bf16 v[54:57], v[158:161], v[194:197], v[54:57]
	v_mfma_f32_16x16x32_bf16 v[50:53], v[150:153], v[202:205], v[50:53]
	v_mfma_f32_16x16x32_bf16 v[46:49], v[158:161], v[202:205], v[46:49]
	v_mfma_f32_16x16x32_bf16 v[42:45], v[150:153], v[210:213], v[42:45]
	v_mfma_f32_16x16x32_bf16 v[38:41], v[158:161], v[210:213], v[38:41]
	v_mfma_f32_16x16x32_bf16 v[66:69], v[154:157], v[190:193], v[66:69]
	v_mfma_f32_16x16x32_bf16 v[62:65], v[162:165], v[190:193], v[62:65]
	v_mfma_f32_16x16x32_bf16 v[58:61], v[154:157], v[198:201], v[58:61]
	v_mfma_f32_16x16x32_bf16 v[54:57], v[162:165], v[198:201], v[54:57]
	v_mfma_f32_16x16x32_bf16 v[50:53], v[154:157], v[206:209], v[50:53]
	v_mfma_f32_16x16x32_bf16 v[46:49], v[162:165], v[206:209], v[46:49]
	v_mfma_f32_16x16x32_bf16 v[42:45], v[154:157], v[214:217], v[42:45]
	v_mfma_f32_16x16x32_bf16 v[38:41], v[162:165], v[214:217], v[38:41]
	s_setprio 0
	s_waitcnt vmcnt(8)
	s_barrier
	s_add_i32 s68, s56, s35
	s_mov_b32 m0, s68
	ds_read_b128 v[186:189], v224 offset:16384
	ds_read_b128 v[190:193], v224 offset:17408
	global_load_lds_dwordx4 v168, s[28:29]
	ds_read_b128 v[194:197], v224 offset:18432
	s_add_i32 m0, s68, 0x2000
	s_add_u32 s68, s28, 0x300000
	s_addc_u32 s69, s29, 0
	s_add_i32 s70, s57, s35
	global_load_lds_dwordx4 v172, s[28:29]
	ds_read_b128 v[198:201], v224 offset:19456
	s_mov_b32 m0, s70
	s_add_u32 s74, s30, s14
	s_addc_u32 s75, s31, s15
	global_load_lds_dwordx4 v168, s[68:69]
	ds_read_b128 v[202:205], v224 offset:20480
	s_add_i32 m0, s70, 0x2000
	s_nop 0
	global_load_lds_dwordx4 v172, s[68:69]
	ds_read_b128 v[206:209], v224 offset:21504
	s_mov_b32 m0, s37
	s_nop 0
	global_load_lds_dwordx4 v166, s[30:31]
	ds_read_b128 v[210:213], v224 offset:22528
	s_mov_b32 m0, s38
	s_nop 0
	global_load_lds_dwordx4 v170, s[30:31]
	ds_read_b128 v[214:217], v224 offset:23552
	s_waitcnt lgkmcnt(0)
	s_barrier
; #define PG8_STAGE(bufoff, gbase, voff) do { _Pragma("unroll") for (int _i = 0; _i < 2; ++_i) \
;         __builtin_amdgcn_global_load_lds((const unsigned*)((const char*)(gbase) + (voff)[_i]), (LAS unsigned*)(lds + (bufoff) + ldsw + _i * 8192), 16, 0, 0); } while (0)
; #define PG8_LDA(dst, b, h) do { _Pragma("unroll") for (int m = 0; m < 4; ++m) _Pragma("unroll") for (int k = 0; k < 2; ++k) dst[m][k] = *(const LAS bf16x8*)(lds + PG8_SA(b, h) + aoff + m * 2048 + k * 1024); } while (0)
; #define PG8_LDB(dst, b, h) do { _Pragma("unroll") for (int n = 0; n < 2; ++n) _Pragma("unroll") for (int k = 0; k < 2; ++k) dst[n][k] = *(const LAS bf16x8*)(lds + PG8_SB(b, h) + boff + n * 2048 + k * 1024); } while (0)
; #define PG8_MMA(ai, bj, At, Bt) do { __builtin_amdgcn_s_setprio(1); _Pragma("unroll") for (int m = 0; m < 4; ++m) _Pragma("unroll") for (int n = 0; n < 2; ++n) _Pragma("unroll") for (int k = 0; k < 2; ++k) \
;         acc[ai][bj][m][n] = __builtin_amdgcn_mfma_f32_16x16x32_bf16(Bt[n][k], At[m][k], acc[ai][bj][m][n], 0, 0, 0); __builtin_amdgcn_s_setprio(0); } while (0)
; #define PG8_WAIT_V(n) asm volatile("s_waitcnt vmcnt(" #n ")" ::: "memory")
; #define PG8_WAIT_L(n) asm volatile("s_waitcnt lgkmcnt(" #n ")" ::: "memory")
; #define PG8_BAR __builtin_amdgcn_s_barrier()
; #define PG8_SCHED __builtin_amdgcn_sched_barrier(0)
; template <class Epi, class Sched, bool ALIGN_EPI, class Hook = NoHook>
; __device__ __forceinline__ void gemm_phase(LAS unsigned char* lds, const Gemm g, const Sched& S, const Epi& E, const Hook& H = Hook()) {
;     ...
;             PG8_LDA(At, 0, 1); PG8_STAGE(PG8_SB(0, 0), b2, voffB); PG8_STAGE(PG8_SB(0, 1), b2 + hB, voffB); PG8_STAGE(PG8_SA(0, 0), a2, voffA);
;             PG8_WAIT_V(8); PG8_WAIT_L(0); PG8_BAR; PG8_MMA(1, 0, At, B0); PG8_MMA(1, 1, At, B1); PG8_BAR; PG8_SCHED;
;             PG8_LDB(B0, 1, 0); PG8_LDB(B1, 1, 1); PG8_SCHED; PG8_LDA(At, 1, 0); PG8_STAGE(PG8_SA(0, 1), a2 + hA, voffA);
;             PG8_WAIT_V(8); PG8_WAIT_L(0); PG8_BAR; PG8_MMA(0, 0, At, B0); PG8_MMA(0, 1, At, B1); PG8_BAR; PG8_SCHED;
;             PG8_LDA(At, 1, 1); PG8_STAGE(PG8_SB(1, 0), b3, voffB); PG8_STAGE(PG8_SB(1, 1), b3 + hB, voffB); PG8_STAGE(PG8_SA(1, 0), a3, voffA);
	s_setprio 1
	s_waitcnt lgkmcnt(0)
	v_mfma_f32_16x16x32_bf16 v[98:101], v[126:129], v[186:189], v[98:101]
	v_mfma_f32_16x16x32_bf16 v[94:97], v[142:145], v[186:189], v[94:97]
	v_mfma_f32_16x16x32_bf16 v[90:93], v[126:129], v[194:197], v[90:93]
	v_mfma_f32_16x16x32_bf16 v[86:89], v[142:145], v[194:197], v[86:89]
	v_mfma_f32_16x16x32_bf16 v[82:85], v[126:129], v[202:205], v[82:85]
	v_mfma_f32_16x16x32_bf16 v[78:81], v[142:145], v[202:205], v[78:81]
	v_mfma_f32_16x16x32_bf16 v[74:77], v[126:129], v[210:213], v[74:77]
	v_mfma_f32_16x16x32_bf16 v[70:73], v[142:145], v[210:213], v[70:73]
	v_mfma_f32_16x16x32_bf16 v[98:101], v[130:133], v[190:193], v[98:101]
	v_mfma_f32_16x16x32_bf16 v[94:97], v[146:149], v[190:193], v[94:97]
	v_mfma_f32_16x16x32_bf16 v[90:93], v[130:133], v[198:201], v[90:93]
	v_mfma_f32_16x16x32_bf16 v[86:89], v[146:149], v[198:201], v[86:89]
	v_mfma_f32_16x16x32_bf16 v[82:85], v[130:133], v[206:209], v[82:85]
	v_mfma_f32_16x16x32_bf16 v[78:81], v[146:149], v[206:209], v[78:81]
	v_mfma_f32_16x16x32_bf16 v[74:77], v[130:133], v[214:217], v[74:77]
	v_mfma_f32_16x16x32_bf16 v[70:73], v[146:149], v[214:217], v[70:73]
	s_setprio 0
	s_setprio 1
	v_mfma_f32_16x16x32_bf16 v[34:37], v[150:153], v[186:189], v[34:37]
	v_mfma_f32_16x16x32_bf16 v[30:33], v[158:161], v[186:189], v[30:33]
	v_mfma_f32_16x16x32_bf16 v[26:29], v[150:153], v[194:197], v[26:29]
	v_mfma_f32_16x16x32_bf16 v[22:25], v[158:161], v[194:197], v[22:25]
	v_mfma_f32_16x16x32_bf16 v[18:21], v[150:153], v[202:205], v[18:21]
	v_mfma_f32_16x16x32_bf16 v[14:17], v[158:161], v[202:205], v[14:17]
	v_mfma_f32_16x16x32_bf16 v[10:13], v[150:153], v[210:213], v[10:13]
	v_mfma_f32_16x16x32_bf16 v[4:7], v[158:161], v[210:213], v[6:9]
	v_mfma_f32_16x16x32_bf16 v[34:37], v[154:157], v[190:193], v[34:37]
	v_mfma_f32_16x16x32_bf16 v[30:33], v[162:165], v[190:193], v[30:33]
	v_mfma_f32_16x16x32_bf16 v[26:29], v[154:157], v[198:201], v[26:29]
	v_mfma_f32_16x16x32_bf16 v[22:25], v[162:165], v[198:201], v[22:25]
	v_mfma_f32_16x16x32_bf16 v[18:21], v[154:157], v[206:209], v[18:21]
	v_mfma_f32_16x16x32_bf16 v[14:17], v[162:165], v[206:209], v[14:17]
	v_mfma_f32_16x16x32_bf16 v[10:13], v[154:157], v[214:217], v[10:13]
	v_mfma_f32_16x16x32_bf16 v[4:7], v[162:165], v[214:217], v[4:7]
	s_setprio 0
	s_waitcnt vmcnt(8)
	s_barrier
	s_add_i32 s68, 0, 0x18000
	v_add_u32_e32 v3, s68, v222
	s_add_i32 s69, 0, 0x1c000
	ds_read_b128 v[126:129], v3
	ds_read_b128 v[130:133], v3 offset:1024
	ds_read_b128 v[142:145], v3 offset:2048
	ds_read_b128 v[146:149], v3 offset:3072
	v_add_u32_e32 v3, s69, v222
	s_add_u32 s30, s30, 0x300000
	s_addc_u32 s31, s31, 0
	s_mov_b32 m0, s39
	s_nop 0
	global_load_lds_dwordx4 v166, s[30:31]
	ds_read_b128 v[150:153], v3
	ds_read_b128 v[154:157], v3 offset:1024
	ds_read_b128 v[158:161], v3 offset:2048
	ds_read_b128 v[162:165], v3 offset:3072
	ds_read_b128 v[186:189], v224 offset:32768
	ds_read_b128 v[190:193], v224 offset:33792
	ds_read_b128 v[194:197], v224 offset:34816
	s_mov_b32 m0, s40
	s_nop 0
	global_load_lds_dwordx4 v170, s[30:31]
	ds_read_b128 v[198:201], v224 offset:35840
	ds_read_b128 v[202:205], v224 offset:36864
	ds_read_b128 v[206:209], v224 offset:37888
	ds_read_b128 v[210:213], v224 offset:38912
	ds_read_b128 v[214:217], v224 offset:39936
	s_waitcnt lgkmcnt(0)
	s_barrier
	s_setprio 1
	s_waitcnt lgkmcnt(0)
	v_mfma_f32_16x16x32_bf16 v[138:141], v[126:129], v[186:189], v[138:141]
	v_mfma_f32_16x16x32_bf16 v[134:137], v[142:145], v[186:189], v[134:137]
	v_mfma_f32_16x16x32_bf16 v[122:125], v[126:129], v[194:197], v[122:125]
	v_mfma_f32_16x16x32_bf16 v[118:121], v[142:145], v[194:197], v[118:121]
	v_mfma_f32_16x16x32_bf16 v[114:117], v[126:129], v[202:205], v[114:117]
	v_mfma_f32_16x16x32_bf16 v[110:113], v[142:145], v[202:205], v[110:113]
	v_mfma_f32_16x16x32_bf16 v[106:109], v[126:129], v[210:213], v[106:109]
	v_mfma_f32_16x16x32_bf16 v[102:105], v[142:145], v[210:213], v[102:105]
	v_mfma_f32_16x16x32_bf16 v[138:141], v[130:133], v[190:193], v[138:141]
	v_mfma_f32_16x16x32_bf16 v[134:137], v[146:149], v[190:193], v[134:137]
	v_mfma_f32_16x16x32_bf16 v[122:125], v[130:133], v[198:201], v[122:125]
	v_mfma_f32_16x16x32_bf16 v[118:121], v[146:149], v[198:201], v[118:121]
	v_mfma_f32_16x16x32_bf16 v[114:117], v[130:133], v[206:209], v[114:117]
	v_mfma_f32_16x16x32_bf16 v[110:113], v[146:149], v[206:209], v[110:113]
	v_mfma_f32_16x16x32_bf16 v[106:109], v[130:133], v[214:217], v[106:109]
	v_mfma_f32_16x16x32_bf16 v[102:105], v[146:149], v[214:217], v[102:105]
	s_setprio 0
	s_setprio 1
	v_mfma_f32_16x16x32_bf16 v[66:69], v[150:153], v[186:189], v[66:69]
	v_mfma_f32_16x16x32_bf16 v[62:65], v[158:161], v[186:189], v[62:65]
	v_mfma_f32_16x16x32_bf16 v[58:61], v[150:153], v[194:197], v[58:61]
	v_mfma_f32_16x16x32_bf16 v[54:57], v[158:161], v[194:197], v[54:57]
	v_mfma_f32_16x16x32_bf16 v[50:53], v[150:153], v[202:205], v[50:53]
	v_mfma_f32_16x16x32_bf16 v[46:49], v[158:161], v[202:205], v[46:49]
	v_mfma_f32_16x16x32_bf16 v[42:45], v[150:153], v[210:213], v[42:45]
	v_mfma_f32_16x16x32_bf16 v[38:41], v[158:161], v[210:213], v[38:41]
	v_mfma_f32_16x16x32_bf16 v[66:69], v[154:157], v[190:193], v[66:69]
	v_mfma_f32_16x16x32_bf16 v[62:65], v[162:165], v[190:193], v[62:65]
	v_mfma_f32_16x16x32_bf16 v[58:61], v[154:157], v[198:201], v[58:61]
	v_mfma_f32_16x16x32_bf16 v[54:57], v[162:165], v[198:201], v[54:57]
	v_mfma_f32_16x16x32_bf16 v[50:53], v[154:157], v[206:209], v[50:53]
	v_mfma_f32_16x16x32_bf16 v[46:49], v[162:165], v[206:209], v[46:49]
	v_mfma_f32_16x16x32_bf16 v[42:45], v[154:157], v[214:217], v[42:45]
	v_mfma_f32_16x16x32_bf16 v[38:41], v[162:165], v[214:217], v[38:41]
	s_setprio 0
	s_waitcnt vmcnt(8)
	s_barrier
; #define PG8_STAGE(bufoff, gbase, voff) do { _Pragma("unroll") for (int _i = 0; _i < 2; ++_i) \
;         __builtin_amdgcn_global_load_lds((const unsigned*)((const char*)(gbase) + (voff)[_i]), (LAS unsigned*)(lds + (bufoff) + ldsw + _i * 8192), 16, 0, 0); } while (0)
; #define PG8_LDA(dst, b, h) do { _Pragma("unroll") for (int m = 0; m < 4; ++m) _Pragma("unroll") for (int k = 0; k < 2; ++k) dst[m][k] = *(const LAS bf16x8*)(lds + PG8_SA(b, h) + aoff + m * 2048 + k * 1024); } while (0)
; #define PG8_MMA(ai, bj, At, Bt) do { __builtin_amdgcn_s_setprio(1); _Pragma("unroll") for (int m = 0; m < 4; ++m) _Pragma("unroll") for (int n = 0; n < 2; ++n) _Pragma("unroll") for (int k = 0; k < 2; ++k) \
;         acc[ai][bj][m][n] = __builtin_amdgcn_mfma_f32_16x16x32_bf16(Bt[n][k], At[m][k], acc[ai][bj][m][n], 0, 0, 0); __builtin_amdgcn_s_setprio(0); } while (0)
; #define PG8_WAIT_V(n) asm volatile("s_waitcnt vmcnt(" #n ")" ::: "memory")
; #define PG8_WAIT_L(n) asm volatile("s_waitcnt lgkmcnt(" #n ")" ::: "memory")
; #define PG8_BAR __builtin_amdgcn_s_barrier()
; #define PG8_SCHED __builtin_amdgcn_sched_barrier(0)
; template <class Epi, class Sched, bool ALIGN_EPI, class Hook = NoHook>
; __device__ __forceinline__ void gemm_phase(LAS unsigned char* lds, const Gemm g, const Sched& S, const Epi& E, const Hook& H = Hook()) {
;     ...
;             PG8_LDA(At, 1, 1); PG8_STAGE(PG8_SB(1, 0), b3, voffB); PG8_STAGE(PG8_SB(1, 1), b3 + hB, voffB); PG8_STAGE(PG8_SA(1, 0), a3, voffA);
;             PG8_WAIT_V(8); PG8_WAIT_L(0); PG8_BAR; PG8_MMA(1, 0, At, B0); PG8_MMA(1, 1, At, B1); PG8_BAR; PG8_SCHED;
;         }
;         if constexpr (Hook::ON) H.after(te, acc, cur, wr, wc, fr, fq);
	s_add_i32 s30, s68, s35
	s_add_u32 s72, s28, s14
	s_addc_u32 s73, s29, s15
	s_mov_b32 m0, s30
	ds_read_b128 v[186:189], v224 offset:49152
	ds_read_b128 v[190:193], v224 offset:50176
	global_load_lds_dwordx4 v168, s[72:73]
	ds_read_b128 v[194:197], v224 offset:51200
	s_add_i32 m0, s30, 0x2000
	s_add_u32 s28, s28, 0x300080
	s_addc_u32 s29, s29, 0
	s_add_i32 s30, s69, s35
	global_load_lds_dwordx4 v172, s[72:73]
	ds_read_b128 v[198:201], v224 offset:52224
	s_mov_b32 m0, s30
	s_nop 0
	global_load_lds_dwordx4 v168, s[28:29]
	ds_read_b128 v[202:205], v224 offset:53248
	s_add_i32 m0, s30, 0x2000
	s_nop 0
	global_load_lds_dwordx4 v172, s[28:29]
	ds_read_b128 v[206:209], v224 offset:54272
	s_mov_b32 m0, s45
	s_nop 0
	global_load_lds_dwordx4 v166, s[74:75]
	ds_read_b128 v[210:213], v224 offset:55296
	s_mov_b32 m0, s46
	s_nop 0
	global_load_lds_dwordx4 v170, s[74:75]
	ds_read_b128 v[214:217], v224 offset:56320
	s_waitcnt lgkmcnt(0)
	s_barrier
	s_setprio 1
	s_waitcnt lgkmcnt(0)
	v_mfma_f32_16x16x32_bf16 v[98:101], v[126:129], v[186:189], v[98:101]
	v_mfma_f32_16x16x32_bf16 v[94:97], v[142:145], v[186:189], v[94:97]
	v_mfma_f32_16x16x32_bf16 v[90:93], v[126:129], v[194:197], v[90:93]
	v_mfma_f32_16x16x32_bf16 v[86:89], v[142:145], v[194:197], v[86:89]
	v_mfma_f32_16x16x32_bf16 v[82:85], v[126:129], v[202:205], v[82:85]
	v_mfma_f32_16x16x32_bf16 v[78:81], v[142:145], v[202:205], v[78:81]
	v_mfma_f32_16x16x32_bf16 v[74:77], v[126:129], v[210:213], v[74:77]
	v_mfma_f32_16x16x32_bf16 v[70:73], v[142:145], v[210:213], v[70:73]
	v_mfma_f32_16x16x32_bf16 v[98:101], v[130:133], v[190:193], v[98:101]
	v_mfma_f32_16x16x32_bf16 v[94:97], v[146:149], v[190:193], v[94:97]
	v_mfma_f32_16x16x32_bf16 v[90:93], v[130:133], v[198:201], v[90:93]
	v_mfma_f32_16x16x32_bf16 v[86:89], v[146:149], v[198:201], v[86:89]
	v_mfma_f32_16x16x32_bf16 v[82:85], v[130:133], v[206:209], v[82:85]
	v_mfma_f32_16x16x32_bf16 v[78:81], v[146:149], v[206:209], v[78:81]
	v_mfma_f32_16x16x32_bf16 v[74:77], v[130:133], v[214:217], v[74:77]
	v_mfma_f32_16x16x32_bf16 v[70:73], v[146:149], v[214:217], v[70:73]
	s_setprio 0
	s_setprio 1
	v_mfma_f32_16x16x32_bf16 v[34:37], v[150:153], v[186:189], v[34:37]
	v_mfma_f32_16x16x32_bf16 v[30:33], v[158:161], v[186:189], v[30:33]
	v_mfma_f32_16x16x32_bf16 v[26:29], v[150:153], v[194:197], v[26:29]
	v_mfma_f32_16x16x32_bf16 v[22:25], v[158:161], v[194:197], v[22:25]
	v_mfma_f32_16x16x32_bf16 v[18:21], v[150:153], v[202:205], v[18:21]
	v_mfma_f32_16x16x32_bf16 v[14:17], v[158:161], v[202:205], v[14:17]
	v_mfma_f32_16x16x32_bf16 v[8:11], v[150:153], v[210:213], v[10:13]
	v_mfma_f32_16x16x32_bf16 v[4:7], v[158:161], v[210:213], v[4:7]
	v_mfma_f32_16x16x32_bf16 v[34:37], v[154:157], v[190:193], v[34:37]
	v_mfma_f32_16x16x32_bf16 v[30:33], v[162:165], v[190:193], v[30:33]
	v_mfma_f32_16x16x32_bf16 v[26:29], v[154:157], v[198:201], v[26:29]
	v_mfma_f32_16x16x32_bf16 v[22:25], v[162:165], v[198:201], v[22:25]
	v_mfma_f32_16x16x32_bf16 v[18:21], v[154:157], v[206:209], v[18:21]
	v_mfma_f32_16x16x32_bf16 v[14:17], v[162:165], v[206:209], v[14:17]
	v_mfma_f32_16x16x32_bf16 v[10:13], v[154:157], v[214:217], v[8:11]
	v_mfma_f32_16x16x32_bf16 v[6:9], v[162:165], v[214:217], v[4:7]
	s_setprio 0
	s_waitcnt vmcnt(8)
	s_barrier
	s_add_u32 s26, s26, 0x100
	s_addc_u32 s27, s27, 0
	s_cmp_ge_u32 s67, s66
	s_cbranch_scc0 .LBB0_783
	s_branch .Lmy_d783X

;     __device__ __forceinline__ void after(int te, f32x4 (&acc)[2][2][4][2], const Unit& u, int wr, int wc, int fr, int fq) const {
;         if (te > D_INNER / BK) return;
;         const int g = (te >> 4) - 1;
;         asm volatile("" : "+v"(fr), "+v"(fq));
; #pragma unroll
;         for (int ai = 0; ai < 2; ++ai)
; #pragma unroll
;             for (int m = 0; m < 4; ++m) { const float f = tab[(ai * HALF + wr * 64 + m * 16 + fr) * 8 + g];
; #pragma unroll
;                 for (int bj = 0; bj < 2; ++bj)
; #pragma unroll
;                     for (int n = 0; n < 2; ++n) acc[ai][bj][m][n] *= f; }
.Lmy_d783X:
	s_cmpk_gt_u32 s65, 0x7f
	s_cbranch_scc1 .LBB0_787
	s_lshr_b32 s26, s66, 4
	s_add_i32 s26, s26, -1
	v_mov_b32_e32 v3, v1
	v_mov_b32_e32 v4, v220
	s_lshl_b32 s27, s26, 2
	s_add_i32 s28, s27, s48
	v_lshlrev_b32_e32 v5, 5, v3
	v_add_u32_e32 v126, s28, v5
	ds_read_b32 v126, v126
	s_add_i32 s28, s27, s49
	s_waitcnt lgkmcnt(0)
	v_pk_mul_f32 v[140:141], v[140:141], v[126:127] op_sel_hi:[1,0]
	v_pk_mul_f32 v[138:139], v[138:139], v[126:127] op_sel_hi:[1,0]
	v_pk_mul_f32 v[136:137], v[136:137], v[126:127] op_sel_hi:[1,0]
	v_pk_mul_f32 v[134:135], v[134:135], v[126:127] op_sel_hi:[1,0]
	v_pk_mul_f32 v[68:69], v[68:69], v[126:127] op_sel_hi:[1,0]
	v_pk_mul_f32 v[66:67], v[66:67], v[126:127] op_sel_hi:[1,0]
	v_pk_mul_f32 v[64:65], v[64:65], v[126:127] op_sel_hi:[1,0]
	v_pk_mul_f32 v[62:63], v[62:63], v[126:127] op_sel_hi:[1,0]
	v_add_u32_e32 v126, s28, v5
	ds_read_b32 v126, v126
	s_add_i32 s28, s27, s50
	s_waitcnt lgkmcnt(0)
	v_pk_mul_f32 v[124:125], v[124:125], v[126:127] op_sel_hi:[1,0]
	v_pk_mul_f32 v[122:123], v[122:123], v[126:127] op_sel_hi:[1,0]
	v_pk_mul_f32 v[120:121], v[120:121], v[126:127] op_sel_hi:[1,0]
	v_pk_mul_f32 v[118:119], v[118:119], v[126:127] op_sel_hi:[1,0]
	v_pk_mul_f32 v[60:61], v[60:61], v[126:127] op_sel_hi:[1,0]
	v_pk_mul_f32 v[58:59], v[58:59], v[126:127] op_sel_hi:[1,0]
	v_pk_mul_f32 v[56:57], v[56:57], v[126:127] op_sel_hi:[1,0]
	v_pk_mul_f32 v[54:55], v[54:55], v[126:127] op_sel_hi:[1,0]
	v_add_u32_e32 v126, s28, v5
	ds_read_b32 v126, v126
	s_add_i32 s28, s27, s51
	s_waitcnt lgkmcnt(0)
	v_pk_mul_f32 v[116:117], v[116:117], v[126:127] op_sel_hi:[1,0]
	v_pk_mul_f32 v[114:115], v[114:115], v[126:127] op_sel_hi:[1,0]
	v_pk_mul_f32 v[112:113], v[112:113], v[126:127] op_sel_hi:[1,0]
	v_pk_mul_f32 v[110:111], v[110:111], v[126:127] op_sel_hi:[1,0]
	v_pk_mul_f32 v[52:53], v[52:53], v[126:127] op_sel_hi:[1,0]
	v_pk_mul_f32 v[50:51], v[50:51], v[126:127] op_sel_hi:[1,0]
	v_pk_mul_f32 v[48:49], v[48:49], v[126:127] op_sel_hi:[1,0]
	v_pk_mul_f32 v[46:47], v[46:47], v[126:127] op_sel_hi:[1,0]
	v_add_u32_e32 v126, s28, v5
	ds_read_b32 v126, v126
	s_add_i32 s28, s27, s52
	s_waitcnt lgkmcnt(0)
	v_pk_mul_f32 v[108:109], v[108:109], v[126:127] op_sel_hi:[1,0]
	v_pk_mul_f32 v[106:107], v[106:107], v[126:127] op_sel_hi:[1,0]
	v_pk_mul_f32 v[104:105], v[104:105], v[126:127] op_sel_hi:[1,0]
	v_pk_mul_f32 v[102:103], v[102:103], v[126:127] op_sel_hi:[1,0]
	v_pk_mul_f32 v[44:45], v[44:45], v[126:127] op_sel_hi:[1,0]
	v_pk_mul_f32 v[42:43], v[42:43], v[126:127] op_sel_hi:[1,0]
	v_pk_mul_f32 v[40:41], v[40:41], v[126:127] op_sel_hi:[1,0]
	v_pk_mul_f32 v[38:39], v[38:39], v[126:127] op_sel_hi:[1,0]
	v_add_u32_e32 v126, s28, v5
	ds_read_b32 v126, v126
	s_add_i32 s28, s27, s53
	s_waitcnt lgkmcnt(0)
	v_pk_mul_f32 v[100:101], v[100:101], v[126:127] op_sel_hi:[1,0]
	v_pk_mul_f32 v[98:99], v[98:99], v[126:127] op_sel_hi:[1,0]
	v_pk_mul_f32 v[96:97], v[96:97], v[126:127] op_sel_hi:[1,0]
	v_pk_mul_f32 v[94:95], v[94:95], v[126:127] op_sel_hi:[1,0]
	v_pk_mul_f32 v[36:37], v[36:37], v[126:127] op_sel_hi:[1,0]
	v_pk_mul_f32 v[34:35], v[34:35], v[126:127] op_sel_hi:[1,0]
	v_pk_mul_f32 v[32:33], v[32:33], v[126:127] op_sel_hi:[1,0]
	v_pk_mul_f32 v[30:31], v[30:31], v[126:127] op_sel_hi:[1,0]
	v_add_u32_e32 v126, s28, v5
	ds_read_b32 v126, v126
	s_add_i32 s28, s27, s54
	s_add_i32 s27, s27, s55
	s_cmp_lg_u32 s26, 7
	s_waitcnt lgkmcnt(0)
	v_pk_mul_f32 v[92:93], v[92:93], v[126:127] op_sel_hi:[1,0]
	v_pk_mul_f32 v[90:91], v[90:91], v[126:127] op_sel_hi:[1,0]
	v_pk_mul_f32 v[88:89], v[88:89], v[126:127] op_sel_hi:[1,0]
	v_pk_mul_f32 v[86:87], v[86:87], v[126:127] op_sel_hi:[1,0]
	v_pk_mul_f32 v[28:29], v[28:29], v[126:127] op_sel_hi:[1,0]
	v_pk_mul_f32 v[26:27], v[26:27], v[126:127] op_sel_hi:[1,0]
	v_pk_mul_f32 v[24:25], v[24:25], v[126:127] op_sel_hi:[1,0]
	v_pk_mul_f32 v[22:23], v[22:23], v[126:127] op_sel_hi:[1,0]
	v_add_u32_e32 v126, s28, v5
	ds_read_b32 v126, v126
	v_add_u32_e32 v5, s27, v5
	s_waitcnt lgkmcnt(0)
	v_pk_mul_f32 v[84:85], v[84:85], v[126:127] op_sel_hi:[1,0]
	v_pk_mul_f32 v[82:83], v[82:83], v[126:127] op_sel_hi:[1,0]
	v_pk_mul_f32 v[80:81], v[80:81], v[126:127] op_sel_hi:[1,0]
	v_pk_mul_f32 v[78:79], v[78:79], v[126:127] op_sel_hi:[1,0]
	v_pk_mul_f32 v[20:21], v[20:21], v[126:127] op_sel_hi:[1,0]
	v_pk_mul_f32 v[18:19], v[18:19], v[126:127] op_sel_hi:[1,0]
	v_pk_mul_f32 v[16:17], v[16:17], v[126:127] op_sel_hi:[1,0]
	v_pk_mul_f32 v[14:15], v[14:15], v[126:127] op_sel_hi:[1,0]
	ds_read_b32 v126, v5
	s_waitcnt lgkmcnt(0)
	v_pk_mul_f32 v[76:77], v[76:77], v[126:127] op_sel_hi:[1,0]
	v_pk_mul_f32 v[74:75], v[74:75], v[126:127] op_sel_hi:[1,0]
	v_pk_mul_f32 v[72:73], v[72:73], v[126:127] op_sel_hi:[1,0]
	v_pk_mul_f32 v[70:71], v[70:71], v[126:127] op_sel_hi:[1,0]
	v_pk_mul_f32 v[12:13], v[12:13], v[126:127] op_sel_hi:[1,0]
	v_pk_mul_f32 v[10:11], v[10:11], v[126:127] op_sel_hi:[1,0]
	v_pk_mul_f32 v[8:9], v[8:9], v[126:127] op_sel_hi:[1,0]
	v_pk_mul_f32 v[6:7], v[6:7], v[126:127] op_sel_hi:[1,0]
	s_cbranch_scc1 .LBB0_787
; __device__ __forceinline__ void unpack8(const u32x4 w, float (&v)[8]) { v[0] = bf_lo(w.x); v[1] = bf_hi(w.x); v[2] = bf_lo(w.y); v[3] = bf_hi(w.y); v[4] = bf_lo(w.z); v[5] = bf_hi(w.z); v[6] = bf_lo(w.w); v[7] = bf_hi(w.w); }
;     __device__ __forceinline__ void after(int te, f32x4 (&acc)[2][2][4][2], const Unit& u, int wr, int wc, int fr, int fq) const {
;     ...
;         if (g == 7) {
;             const int row0 = u.pm * BM + wr * 64 + fr, col0 = u.pn * BM + wc * 32 + 8 * fq;
; #pragma unroll
;             for (int bj = 0; bj < 2; ++bj) { const int c = col0 + bj * HALF;
;                 const f32x4 s0 = *(const f32x4*)(gb + c), s1 = *(const f32x4*)(gb + c + 4), a0 = *(const f32x4*)(gb + D_MODEL + c), a1 = *(const f32x4*)(gb + D_MODEL + c + 4);
; #pragma unroll
;                 for (int ai = 0; ai < 2; ++ai) {
;                     u32x4 gs[4], ga[4];
; #pragma unroll
;                     for (int m = 0; m < 4; ++m) { const size_t r = (size_t)(row0 + ai * HALF + m * 16); gs[m] = *(const u32x4*)(proj + r * LDP + PGS + c); ga[m] = *(const u32x4*)(proj + r * LDP + PGA + c); }
; #pragma unroll
;                     for (int m = 0; m < 4; ++m) { float vs[8], va[8]; unpack8(gs[m], vs); unpack8(ga[m], va);
; #pragma unroll
;                         for (int e = 0; e < 4; ++e) {
;                             acc[ai][bj][m][0][e] *= (1.f + __expf(-(va[e] + a0[e]))) * __builtin_amdgcn_rcpf(1.f + __expf(-(vs[e] + s0[e])));
;                             acc[ai][bj][m][1][e] *= (1.f + __expf(-(va[4 + e] + a1[e]))) * __builtin_amdgcn_rcpf(1.f + __expf(-(vs[4 + e] + s1[e]))); } }
	v_add_u32_e32 v126, s62, v3
	v_ashrrev_i32_e32 v127, 31, v126
	v_lshl_add_u32 v4, v4, 3, s61
	v_lshlrev_b64 v[126:127], 14, v[126:127]
	v_ashrrev_i32_e32 v5, 31, v4
	v_lshl_add_u64 v[126:127], s[76:77], 0, v[126:127]
	v_lshl_add_u64 v[192:193], v[4:5], 1, v[126:127]
	v_readlane_b32 s68, v254, 20
	global_load_dwordx4 v[204:207], v[192:193], off
	v_add_co_u32_e32 v126, vcc, s41, v192
	v_lshlrev_b64 v[4:5], 2, v[4:5]
	v_readlane_b32 s70, v254, 22
	v_readlane_b32 s71, v254, 23
	v_addc_co_u32_e32 v127, vcc, 0, v193, vcc
	s_nop 0
	v_lshl_add_u64 v[196:197], s[70:71], 0, v[4:5]
	global_load_dwordx4 v[208:211], v[126:127], off
	global_load_dwordx4 v[142:145], v[196:197], off
	s_nop 0
	global_load_dwordx4 v[126:129], v[196:197], off offset:16
	v_lshl_add_u64 v[198:199], s[12:13], 0, v[4:5]
	global_load_dwordx4 v[146:149], v[198:199], off
	global_load_dwordx4 v[130:133], v[198:199], off offset:16
	s_mov_b64 s[26:27], 0x40000
	v_lshl_add_u64 v[4:5], v[192:193], 0, s[26:27]
	s_mov_b32 s26, 0x40000
	v_add_co_u32_e32 v150, vcc, s26, v192
	s_mov_b64 s[26:27], 0x42000
	s_nop 0
	v_addc_co_u32_e32 v151, vcc, 0, v193, vcc
	v_lshl_add_u64 v[186:187], v[192:193], 0, s[26:27]
	s_mov_b32 s26, 0x42000
	v_add_co_u32_e32 v152, vcc, s26, v192
	s_mov_b64 s[26:27], 0x80000
	s_nop 0
	v_addc_co_u32_e32 v153, vcc, 0, v193, vcc
	v_lshl_add_u64 v[188:189], v[192:193], 0, s[26:27]
	s_mov_b32 s26, 0x80000
	v_add_co_u32_e32 v154, vcc, s26, v192
	s_mov_b64 s[26:27], 0x82000
	s_nop 0
	v_addc_co_u32_e32 v155, vcc, 0, v193, vcc
	v_lshl_add_u64 v[190:191], v[192:193], 0, s[26:27]
	s_mov_b32 s26, 0x82000
	v_add_co_u32_e32 v156, vcc, s26, v192
	s_mov_b64 s[26:27], 0xc0000
	s_nop 0
	v_addc_co_u32_e32 v157, vcc, 0, v193, vcc
	v_lshl_add_u64 v[194:195], v[192:193], 0, s[26:27]
	s_mov_b32 s26, 0xc0000
	v_add_co_u32_e32 v228, vcc, s26, v192
	s_mov_b64 s[26:27], 0xc2000
	s_nop 0
	v_addc_co_u32_e32 v229, vcc, 0, v193, vcc
	v_lshl_add_u64 v[200:201], v[192:193], 0, s[26:27]
	s_mov_b32 s26, 0xc2000
	v_add_co_u32_e32 v230, vcc, s26, v192
	s_mov_b32 s26, 0x200000
	s_nop 0
	v_addc_co_u32_e32 v231, vcc, 0, v193, vcc
	global_load_dwordx4 v[212:215], v[150:151], off
	global_load_dwordx4 v[216:219], v[152:153], off
	global_load_dwordx4 v[162:165], v[154:155], off
	global_load_dwordx4 v[158:161], v[156:157], off
	s_nop 0
	global_load_dwordx4 v[154:157], v[228:229], off
	global_load_dwordx4 v[150:153], v[230:231], off
	v_lshl_add_u64 v[202:203], v[192:193], 0, s[18:19]
	v_readlane_b32 s76, v254, 28
	v_readlane_b32 s77, v254, 29
	v_readlane_b32 s76, v255, 8
	v_readlane_b32 s77, v255, 9
	v_readlane_b32 s69, v254, 21
	v_readlane_b32 s72, v254, 24
	v_readlane_b32 s73, v254, 25
	v_readlane_b32 s74, v254, 26
	v_readlane_b32 s75, v254, 27
	v_readlane_b32 s78, v254, 30
	v_readlane_b32 s79, v254, 31
	v_readlane_b32 s80, v254, 32
	v_readlane_b32 s81, v254, 33
	v_readlane_b32 s82, v254, 34
	v_readlane_b32 s83, v254, 35
	s_waitcnt vmcnt(0)
	v_lshlrev_b32_e32 v3, 16, v204
	v_and_b32_e32 v204, 0xffff0000, v204
	v_lshlrev_b32_e32 v225, 16, v205
	v_and_b32_e32 v227, 0xffff0000, v205
	v_lshlrev_b32_e32 v205, 16, v206
	v_and_b32_e32 v228, 0xffff0000, v206
	v_lshlrev_b32_e32 v229, 16, v207
	v_and_b32_e32 v233, 0xffff0000, v207
	v_add_f32_e32 v3, v142, v3
	v_add_f32_e32 v204, v143, v204
	v_mul_f32_e32 v3, 0xbfb8aa3b, v3
	v_mul_f32_e32 v204, 0xbfb8aa3b, v204
	v_exp_f32_e32 v3, v3
	v_lshlrev_b32_e32 v230, 16, v209
	v_and_b32_e32 v231, 0xffff0000, v209
	v_exp_f32_e32 v209, v204
	v_lshlrev_b32_e32 v206, 16, v208
	v_and_b32_e32 v207, 0xffff0000, v208
	v_lshlrev_b32_e32 v208, 16, v210
	v_add_f32_e32 v206, v146, v206
	v_add_f32_e32 v208, v130, v208
	v_mul_f32_e32 v206, 0xbfb8aa3b, v206
	v_mul_f32_e32 v208, 0xbfb8aa3b, v208
	v_add_f32_e32 v3, 1.0, v3
	v_exp_f32_e32 v204, v206
	v_exp_f32_e32 v206, v208
	v_rcp_f32_e32 v208, v3
	v_add_f32_e32 v3, 1.0, v209
	v_rcp_f32_e32 v209, v3
	v_add_f32_e32 v3, v127, v228
	v_mul_f32_e32 v3, 0xbfb8aa3b, v3
	v_exp_f32_e32 v3, v3
	v_lshlrev_b32_e32 v234, 16, v211
	v_and_b32_e32 v235, 0xffff0000, v211
	v_add_f32_e32 v205, v126, v205
	v_add_f32_e32 v3, 1.0, v3
	v_rcp_f32_e32 v211, v3
	v_add_f32_e32 v3, v144, v225
	v_mul_f32_e32 v3, 0xbfb8aa3b, v3
	v_exp_f32_e32 v3, v3
	v_mul_f32_e32 v205, 0xbfb8aa3b, v205
	v_exp_f32_e32 v205, v205
	v_add_f32_e32 v225, v148, v230
	v_add_f32_e32 v3, 1.0, v3
	v_rcp_f32_e32 v230, v3
	v_add_f32_e32 v3, v128, v229
	v_mul_f32_e32 v3, 0xbfb8aa3b, v3
	v_add_f32_e32 v227, v145, v227
	v_mul_f32_e32 v225, 0xbfb8aa3b, v225
	v_exp_f32_e32 v3, v3
	v_mul_f32_e32 v227, 0xbfb8aa3b, v227
	v_add_f32_e32 v207, v147, v207
	v_exp_f32_e32 v228, v225
	v_add_f32_e32 v225, v132, v234
	v_exp_f32_e32 v227, v227
	v_and_b32_e32 v232, 0xffff0000, v210
	v_mul_f32_e32 v207, 0xbfb8aa3b, v207
	v_add_f32_e32 v205, 1.0, v205
	v_mul_f32_e32 v225, 0xbfb8aa3b, v225
	v_rcp_f32_e32 v210, v205
	v_exp_f32_e32 v205, v207
	v_add_f32_e32 v207, v131, v232
	v_exp_f32_e32 v232, v225
	v_add_f32_e32 v225, v149, v231
	v_add_f32_e32 v3, 1.0, v3
	v_mul_f32_e32 v225, 0xbfb8aa3b, v225
	v_exp_f32_e32 v229, v225
	v_rcp_f32_e32 v234, v3
	v_add_f32_e32 v3, 1.0, v227
	v_rcp_f32_e32 v231, v3
	v_pk_add_f32 v[228:229], v[228:229], 1.0 op_sel_hi:[1,0]
	v_pk_add_f32 v[204:205], v[204:205], 1.0 op_sel_hi:[1,0]
	v_add_f32_e32 v3, v133, v235
	v_pk_mul_f32 v[204:205], v[204:205], v[208:209]
	v_pk_mul_f32 v[208:209], v[228:229], v[230:231]
	v_mul_f32_e32 v3, 0xbfb8aa3b, v3
	v_pk_mul_f32 v[140:141], v[140:141], v[208:209]
	v_add_f32_e32 v208, v129, v233
	v_mul_f32_e32 v208, 0xbfb8aa3b, v208
	v_exp_f32_e32 v208, v208
	v_exp_f32_e32 v233, v3
	v_mul_f32_e32 v207, 0xbfb8aa3b, v207
	v_exp_f32_e32 v207, v207
	v_add_f32_e32 v3, 1.0, v208
; __device__ __forceinline__ void unpack8(const u32x4 w, float (&v)[8]) { v[0] = bf_lo(w.x); v[1] = bf_hi(w.x); v[2] = bf_lo(w.y); v[3] = bf_hi(w.y); v[4] = bf_lo(w.z); v[5] = bf_hi(w.z); v[6] = bf_lo(w.w); v[7] = bf_hi(w.w); }
;     __device__ __forceinline__ void after(int te, f32x4 (&acc)[2][2][4][2], const Unit& u, int wr, int wc, int fr, int fq) const {
;     ...
;             for (int bj = 0; bj < 2; ++bj) { const int c = col0 + bj * HALF;
;                 const f32x4 s0 = *(const f32x4*)(gb + c), s1 = *(const f32x4*)(gb + c + 4), a0 = *(const f32x4*)(gb + D_MODEL + c), a1 = *(const f32x4*)(gb + D_MODEL + c + 4);
; #pragma unroll
;                 for (int ai = 0; ai < 2; ++ai) {
;                     u32x4 gs[4], ga[4];
; #pragma unroll
;                     for (int m = 0; m < 4; ++m) { const size_t r = (size_t)(row0 + ai * HALF + m * 16); gs[m] = *(const u32x4*)(proj + r * LDP + PGS + c); ga[m] = *(const u32x4*)(proj + r * LDP + PGA + c); }
; #pragma unroll
;                     for (int m = 0; m < 4; ++m) { float vs[8], va[8]; unpack8(gs[m], vs); unpack8(ga[m], va);
; #pragma unroll
;                         for (int e = 0; e < 4; ++e) {
;                             acc[ai][bj][m][0][e] *= (1.f + __expf(-(va[e] + a0[e]))) * __builtin_amdgcn_rcpf(1.f + __expf(-(vs[e] + s0[e])));
;                             acc[ai][bj][m][1][e] *= (1.f + __expf(-(va[4 + e] + a1[e]))) * __builtin_amdgcn_rcpf(1.f + __expf(-(vs[4 + e] + s1[e]))); } }
	v_rcp_f32_e32 v235, v3
	v_lshlrev_b32_e32 v3, 16, v212
	v_add_f32_e32 v3, v142, v3
	v_mul_f32_e32 v3, 0xbfb8aa3b, v3
	v_exp_f32_e32 v3, v3
	v_pk_add_f32 v[206:207], v[206:207], 1.0 op_sel_hi:[1,0]
	v_pk_mul_f32 v[138:139], v[138:139], v[204:205]
	v_pk_mul_f32 v[206:207], v[206:207], v[210:211]
	v_add_f32_e32 v3, 1.0, v3
	v_pk_mul_f32 v[134:135], v[134:135], v[206:207]
	v_lshlrev_b32_e32 v207, 16, v214
	v_rcp_f32_e32 v206, v3
	v_add_f32_e32 v3, v126, v207
	v_mul_f32_e32 v3, 0xbfb8aa3b, v3
	v_exp_f32_e32 v3, v3
	v_pk_add_f32 v[204:205], v[232:233], 1.0 op_sel_hi:[1,0]
	v_lshlrev_b32_e32 v208, 16, v218
	v_pk_mul_f32 v[204:205], v[204:205], v[234:235]
	v_add_f32_e32 v3, 1.0, v3
	v_pk_mul_f32 v[136:137], v[136:137], v[204:205]
	v_and_b32_e32 v205, 0xffff0000, v212
	v_rcp_f32_e32 v210, v3
	v_add_f32_e32 v3, v143, v205
	v_mul_f32_e32 v3, 0xbfb8aa3b, v3
	v_exp_f32_e32 v3, v3
	v_add_f32_e32 v207, v130, v208
	v_and_b32_e32 v209, 0xffff0000, v214
	v_mul_f32_e32 v207, 0xbfb8aa3b, v207
	v_add_f32_e32 v3, 1.0, v3
	v_exp_f32_e32 v208, v207
	v_rcp_f32_e32 v207, v3
	v_add_f32_e32 v3, v127, v209
	v_mul_f32_e32 v3, 0xbfb8aa3b, v3
	v_exp_f32_e32 v3, v3
	v_lshlrev_b32_e32 v212, 16, v213
	v_and_b32_e32 v211, 0xffff0000, v216
	v_add_f32_e32 v205, v147, v211
	v_add_f32_e32 v3, 1.0, v3
	v_rcp_f32_e32 v211, v3
	v_add_f32_e32 v3, v144, v212
	v_mul_f32_e32 v3, 0xbfb8aa3b, v3
	v_exp_f32_e32 v3, v3
	v_lshlrev_b32_e32 v225, 16, v215
	v_lshlrev_b32_e32 v214, 16, v217
	v_and_b32_e32 v213, 0xffff0000, v213
	v_add_f32_e32 v3, 1.0, v3
	v_add_f32_e32 v212, v148, v214
	v_rcp_f32_e32 v214, v3
	v_add_f32_e32 v3, v128, v225
	v_mul_f32_e32 v3, 0xbfb8aa3b, v3
	v_add_f32_e32 v213, v145, v213
	v_and_b32_e32 v227, 0xffff0000, v215
	v_lshlrev_b32_e32 v204, 16, v216
	v_and_b32_e32 v215, 0xffff0000, v217
	v_and_b32_e32 v216, 0xffff0000, v218
	v_lshlrev_b32_e32 v217, 16, v219
	v_exp_f32_e32 v3, v3
	v_mul_f32_e32 v213, 0xbfb8aa3b, v213
	v_add_f32_e32 v209, v131, v216
	v_add_f32_e32 v216, v132, v217
	v_exp_f32_e32 v217, v213
	v_add_f32_e32 v204, v146, v204
	v_add_f32_e32 v215, v149, v215
	v_mul_f32_e32 v204, 0xbfb8aa3b, v204
	v_mul_f32_e32 v205, 0xbfb8aa3b, v205
	v_mul_f32_e32 v212, 0xbfb8aa3b, v212
	v_add_f32_e32 v3, 1.0, v3
	v_mul_f32_e32 v213, 0xbfb8aa3b, v215
	v_exp_f32_e32 v204, v204
	v_exp_f32_e32 v205, v205
	v_exp_f32_e32 v212, v212
	v_exp_f32_e32 v213, v213
	v_rcp_f32_e32 v218, v3
	v_add_f32_e32 v3, 1.0, v217
	v_rcp_f32_e32 v215, v3
	v_pk_add_f32 v[212:213], v[212:213], 1.0 op_sel_hi:[1,0]
	v_pk_add_f32 v[204:205], v[204:205], 1.0 op_sel_hi:[1,0]
	v_and_b32_e32 v219, 0xffff0000, v219
	v_pk_mul_f32 v[204:205], v[204:205], v[206:207]
	v_pk_mul_f32 v[206:207], v[212:213], v[214:215]
	v_add_f32_e32 v3, v133, v219
	v_pk_mul_f32 v[124:125], v[124:125], v[206:207]
	v_add_f32_e32 v206, v129, v227
	v_mul_f32_e32 v206, 0xbfb8aa3b, v206
	v_exp_f32_e32 v206, v206
	v_mul_f32_e32 v3, 0xbfb8aa3b, v3
	v_exp_f32_e32 v217, v3
	v_mul_f32_e32 v216, 0xbfb8aa3b, v216
	v_add_f32_e32 v3, 1.0, v206
	v_rcp_f32_e32 v219, v3
	v_lshlrev_b32_e32 v3, 16, v162
	v_mul_f32_e32 v209, 0xbfb8aa3b, v209
	v_exp_f32_e32 v216, v216
	v_add_f32_e32 v3, v142, v3
	v_exp_f32_e32 v209, v209
	v_mul_f32_e32 v3, 0xbfb8aa3b, v3
	v_exp_f32_e32 v3, v3
	v_pk_mul_f32 v[122:123], v[122:123], v[204:205]
	v_pk_add_f32 v[204:205], v[216:217], 1.0 op_sel_hi:[1,0]
	v_pk_add_f32 v[206:207], v[208:209], 1.0 op_sel_hi:[1,0]
	v_pk_mul_f32 v[204:205], v[204:205], v[218:219]
	v_pk_mul_f32 v[206:207], v[206:207], v[210:211]
	v_pk_mul_f32 v[120:121], v[120:121], v[204:205]
	v_and_b32_e32 v204, 0xffff0000, v162
	v_lshlrev_b32_e32 v162, 16, v164
	v_add_f32_e32 v3, 1.0, v3
	v_pk_mul_f32 v[118:119], v[118:119], v[206:207]
	v_lshlrev_b32_e32 v206, 16, v159
	v_and_b32_e32 v210, 0xffff0000, v159
	v_lshlrev_b32_e32 v159, 16, v160
	v_and_b32_e32 v211, 0xffff0000, v160
	v_rcp_f32_e32 v160, v3
	v_add_f32_e32 v3, v126, v162
	v_mul_f32_e32 v3, 0xbfb8aa3b, v3
	v_exp_f32_e32 v3, v3
	v_lshlrev_b32_e32 v205, 16, v163
	v_and_b32_e32 v207, 0xffff0000, v163
	v_and_b32_e32 v163, 0xffff0000, v164
	v_lshlrev_b32_e32 v164, 16, v158
	v_add_f32_e32 v3, 1.0, v3
	v_lshlrev_b32_e32 v208, 16, v165
	v_and_b32_e32 v209, 0xffff0000, v165
	v_and_b32_e32 v165, 0xffff0000, v158
	v_add_f32_e32 v158, v146, v164
	v_rcp_f32_e32 v164, v3
	v_add_f32_e32 v3, v143, v204
	v_mul_f32_e32 v3, 0xbfb8aa3b, v3
	v_exp_f32_e32 v3, v3
	v_lshlrev_b32_e32 v212, 16, v161
	v_and_b32_e32 v213, 0xffff0000, v161
	v_add_f32_e32 v159, v130, v159
	v_add_f32_e32 v3, 1.0, v3
	v_rcp_f32_e32 v161, v3
	v_add_f32_e32 v3, v127, v163
	v_mul_f32_e32 v3, 0xbfb8aa3b, v3
	v_exp_f32_e32 v3, v3
	v_mul_f32_e32 v159, 0xbfb8aa3b, v159
	v_exp_f32_e32 v162, v159
	v_add_f32_e32 v159, v147, v165
	v_add_f32_e32 v3, 1.0, v3
	v_rcp_f32_e32 v165, v3
	v_add_f32_e32 v3, v144, v205
	v_mul_f32_e32 v3, 0xbfb8aa3b, v3
	v_exp_f32_e32 v3, v3
	v_add_f32_e32 v204, v148, v206
	v_add_f32_e32 v207, v145, v207
	v_mul_f32_e32 v207, 0xbfb8aa3b, v207
	v_add_f32_e32 v3, 1.0, v3
	v_rcp_f32_e32 v206, v3
	v_add_f32_e32 v3, v128, v208
	v_mul_f32_e32 v3, 0xbfb8aa3b, v3
	v_exp_f32_e32 v3, v3
	v_add_f32_e32 v205, v132, v212
	v_exp_f32_e32 v207, v207
	v_mul_f32_e32 v205, 0xbfb8aa3b, v205
	v_exp_f32_e32 v208, v205
	v_add_f32_e32 v205, v149, v210
	v_mul_f32_e32 v158, 0xbfb8aa3b, v158
	v_mul_f32_e32 v159, 0xbfb8aa3b, v159
	v_mul_f32_e32 v204, 0xbfb8aa3b, v204
	v_add_f32_e32 v3, 1.0, v3
	v_mul_f32_e32 v205, 0xbfb8aa3b, v205
	v_exp_f32_e32 v158, v158
	v_exp_f32_e32 v159, v159
	v_exp_f32_e32 v204, v204
	v_exp_f32_e32 v205, v205
	v_rcp_f32_e32 v210, v3
	v_add_f32_e32 v3, 1.0, v207
	v_rcp_f32_e32 v207, v3
	v_pk_add_f32 v[204:205], v[204:205], 1.0 op_sel_hi:[1,0]
; __device__ __forceinline__ void unpack8(const u32x4 w, float (&v)[8]) { v[0] = bf_lo(w.x); v[1] = bf_hi(w.x); v[2] = bf_lo(w.y); v[3] = bf_hi(w.y); v[4] = bf_lo(w.z); v[5] = bf_hi(w.z); v[6] = bf_lo(w.w); v[7] = bf_hi(w.w); }
;     __device__ __forceinline__ void after(int te, f32x4 (&acc)[2][2][4][2], const Unit& u, int wr, int wc, int fr, int fq) const {
;     ...
;             for (int bj = 0; bj < 2; ++bj) { const int c = col0 + bj * HALF;
;                 const f32x4 s0 = *(const f32x4*)(gb + c), s1 = *(const f32x4*)(gb + c + 4), a0 = *(const f32x4*)(gb + D_MODEL + c), a1 = *(const f32x4*)(gb + D_MODEL + c + 4);
; #pragma unroll
;                 for (int ai = 0; ai < 2; ++ai) {
;                     u32x4 gs[4], ga[4];
; #pragma unroll
;                     for (int m = 0; m < 4; ++m) { const size_t r = (size_t)(row0 + ai * HALF + m * 16); gs[m] = *(const u32x4*)(proj + r * LDP + PGS + c); ga[m] = *(const u32x4*)(proj + r * LDP + PGA + c); }
; #pragma unroll
;                     for (int m = 0; m < 4; ++m) { float vs[8], va[8]; unpack8(gs[m], vs); unpack8(ga[m], va);
; #pragma unroll
;                         for (int e = 0; e < 4; ++e) {
;                             acc[ai][bj][m][0][e] *= (1.f + __expf(-(va[e] + a0[e]))) * __builtin_amdgcn_rcpf(1.f + __expf(-(vs[e] + s0[e])));
;                             acc[ai][bj][m][1][e] *= (1.f + __expf(-(va[4 + e] + a1[e]))) * __builtin_amdgcn_rcpf(1.f + __expf(-(vs[4 + e] + s1[e]))); } }
	v_pk_add_f32 v[158:159], v[158:159], 1.0 op_sel_hi:[1,0]
	v_add_f32_e32 v3, v133, v213
	v_pk_mul_f32 v[158:159], v[158:159], v[160:161]
	v_pk_mul_f32 v[160:161], v[204:205], v[206:207]
	v_mul_f32_e32 v3, 0xbfb8aa3b, v3
	v_pk_mul_f32 v[116:117], v[116:117], v[160:161]
	v_add_f32_e32 v160, v129, v209
	v_mul_f32_e32 v160, 0xbfb8aa3b, v160
	v_exp_f32_e32 v160, v160
	v_exp_f32_e32 v209, v3
	v_add_f32_e32 v163, v131, v211
	v_mul_f32_e32 v163, 0xbfb8aa3b, v163
	v_add_f32_e32 v3, 1.0, v160
	v_rcp_f32_e32 v211, v3
	v_lshlrev_b32_e32 v3, 16, v154
	v_add_f32_e32 v3, v142, v3
	v_exp_f32_e32 v163, v163
	v_mul_f32_e32 v3, 0xbfb8aa3b, v3
	v_exp_f32_e32 v3, v3
	v_pk_mul_f32 v[114:115], v[114:115], v[158:159]
	v_pk_add_f32 v[158:159], v[208:209], 1.0 op_sel_hi:[1,0]
	v_pk_add_f32 v[160:161], v[162:163], 1.0 op_sel_hi:[1,0]
	v_pk_mul_f32 v[158:159], v[158:159], v[210:211]
	v_pk_mul_f32 v[160:161], v[160:161], v[164:165]
	v_pk_mul_f32 v[112:113], v[112:113], v[158:159]
	v_and_b32_e32 v158, 0xffff0000, v154
	v_lshlrev_b32_e32 v154, 16, v156
	v_add_f32_e32 v3, 1.0, v3
	v_pk_mul_f32 v[110:111], v[110:111], v[160:161]
	v_lshlrev_b32_e32 v160, 16, v151
	v_and_b32_e32 v204, 0xffff0000, v151
	v_lshlrev_b32_e32 v151, 16, v152
	v_and_b32_e32 v162, 0xffff0000, v152
	v_rcp_f32_e32 v152, v3
	v_add_f32_e32 v3, v126, v154
	v_mul_f32_e32 v3, 0xbfb8aa3b, v3
	v_exp_f32_e32 v3, v3
	v_lshlrev_b32_e32 v159, 16, v155
	v_and_b32_e32 v161, 0xffff0000, v155
	v_and_b32_e32 v155, 0xffff0000, v156
	v_lshlrev_b32_e32 v156, 16, v150
	v_add_f32_e32 v3, 1.0, v3
	v_lshlrev_b32_e32 v164, 16, v157
	v_and_b32_e32 v165, 0xffff0000, v157
	v_and_b32_e32 v157, 0xffff0000, v150
	v_add_f32_e32 v150, v146, v156
	v_rcp_f32_e32 v156, v3
	v_add_f32_e32 v3, v143, v158
	v_mul_f32_e32 v3, 0xbfb8aa3b, v3
	v_exp_f32_e32 v3, v3
	v_lshlrev_b32_e32 v205, 16, v153
	v_and_b32_e32 v206, 0xffff0000, v153
	v_add_f32_e32 v151, v130, v151
	v_add_f32_e32 v3, 1.0, v3
	v_rcp_f32_e32 v153, v3
	v_add_f32_e32 v3, v127, v155
	v_add_f32_e32 v155, v131, v162
	v_add_co_u32_e32 v162, vcc, s26, v192
	v_mul_f32_e32 v3, 0xbfb8aa3b, v3
	s_nop 0
	v_addc_co_u32_e32 v163, vcc, 0, v193, vcc
	global_load_dwordx4 v[228:231], v[162:163], off
	v_exp_f32_e32 v3, v3
	v_mul_f32_e32 v151, 0xbfb8aa3b, v151
	s_mov_b32 s26, 0x202000
	v_exp_f32_e32 v154, v151
	v_add_f32_e32 v3, 1.0, v3
	v_add_f32_e32 v151, v147, v157
	v_rcp_f32_e32 v157, v3
	v_add_f32_e32 v3, v144, v159
	v_add_co_u32_e32 v162, vcc, s26, v192
	v_mul_f32_e32 v3, 0xbfb8aa3b, v3
	s_nop 0
	v_addc_co_u32_e32 v163, vcc, 0, v193, vcc
	v_exp_f32_e32 v3, v3
	global_load_dwordx4 v[232:235], v[162:163], off
	v_add_f32_e32 v158, v148, v160
	v_add_f32_e32 v161, v145, v161
	v_add_f32_e32 v3, 1.0, v3
	v_rcp_f32_e32 v160, v3
	v_add_f32_e32 v3, v128, v164
	v_mul_f32_e32 v3, 0xbfb8aa3b, v3
	v_exp_f32_e32 v3, v3
	v_mul_f32_e32 v161, 0xbfb8aa3b, v161
	v_add_f32_e32 v159, v132, v205
	v_exp_f32_e32 v161, v161
	v_mul_f32_e32 v159, 0xbfb8aa3b, v159
	v_exp_f32_e32 v162, v159
	v_add_f32_e32 v159, v149, v204
	v_mul_f32_e32 v150, 0xbfb8aa3b, v150
	v_mul_f32_e32 v151, 0xbfb8aa3b, v151
	v_mul_f32_e32 v158, 0xbfb8aa3b, v158
	v_add_f32_e32 v3, 1.0, v3
	v_mul_f32_e32 v159, 0xbfb8aa3b, v159
	v_exp_f32_e32 v150, v150
	v_exp_f32_e32 v151, v151
	v_exp_f32_e32 v158, v158
	v_exp_f32_e32 v159, v159
	v_rcp_f32_e32 v164, v3
	v_add_f32_e32 v3, 1.0, v161
	v_rcp_f32_e32 v161, v3
	v_pk_add_f32 v[158:159], v[158:159], 1.0 op_sel_hi:[1,0]
	v_pk_add_f32 v[150:151], v[150:151], 1.0 op_sel_hi:[1,0]
	v_add_f32_e32 v3, v133, v206
	v_pk_mul_f32 v[150:151], v[150:151], v[152:153]
	v_pk_mul_f32 v[152:153], v[158:159], v[160:161]
	v_mul_f32_e32 v3, 0xbfb8aa3b, v3
	v_pk_mul_f32 v[108:109], v[108:109], v[152:153]
	v_add_f32_e32 v152, v129, v165
	v_mul_f32_e32 v152, 0xbfb8aa3b, v152
	v_exp_f32_e32 v152, v152
	v_exp_f32_e32 v163, v3
	v_mul_f32_e32 v155, 0xbfb8aa3b, v155
	v_exp_f32_e32 v155, v155
	v_add_f32_e32 v3, 1.0, v152
	v_rcp_f32_e32 v165, v3
	s_mov_b64 s[26:27], 0x200000
	v_lshl_add_u64 v[218:219], v[192:193], 0, s[26:27]
	s_mov_b64 s[26:27], 0x202000
	v_pk_mul_f32 v[106:107], v[106:107], v[150:151]
	v_pk_add_f32 v[150:151], v[162:163], 1.0 op_sel_hi:[1,0]
	v_lshl_add_u64 v[216:217], v[192:193], 0, s[26:27]
	s_mov_b64 s[26:27], 0x240000
	v_pk_mul_f32 v[150:151], v[150:151], v[164:165]
	v_lshl_add_u64 v[204:205], v[192:193], 0, s[26:27]
	s_mov_b32 s26, 0x240000
	v_pk_add_f32 v[152:153], v[154:155], 1.0 op_sel_hi:[1,0]
	v_pk_mul_f32 v[104:105], v[104:105], v[150:151]
	v_add_co_u32_e32 v150, vcc, s26, v192
	s_mov_b64 s[26:27], 0x242000
	v_pk_mul_f32 v[152:153], v[152:153], v[156:157]
	v_addc_co_u32_e32 v151, vcc, 0, v193, vcc
	v_lshl_add_u64 v[206:207], v[192:193], 0, s[26:27]
	s_mov_b32 s26, 0x242000
	v_pk_mul_f32 v[102:103], v[102:103], v[152:153]
	v_add_co_u32_e32 v152, vcc, s26, v192
	s_mov_b64 s[26:27], 0x280000
	s_nop 0
	v_addc_co_u32_e32 v153, vcc, 0, v193, vcc
	global_load_dwordx4 v[236:239], v[150:151], off
	global_load_dwordx4 v[240:243], v[152:153], off
	s_waitcnt vmcnt(3)
	v_lshlrev_b32_e32 v3, 16, v228
	v_add_f32_e32 v3, v142, v3
	v_mul_f32_e32 v3, 0xbfb8aa3b, v3
	v_exp_f32_e32 v3, v3
	v_lshlrev_b32_e32 v227, 16, v229
	v_and_b32_e32 v245, 0xffff0000, v229
	v_lshlrev_b32_e32 v229, 16, v230
	v_add_f32_e32 v3, 1.0, v3
	v_and_b32_e32 v246, 0xffff0000, v230
	v_rcp_f32_e32 v230, v3
	v_add_f32_e32 v3, v126, v229
	v_mul_f32_e32 v3, 0xbfb8aa3b, v3
	v_exp_f32_e32 v3, v3
	v_lshl_add_u64 v[208:209], v[192:193], 0, s[26:27]
	s_mov_b32 s26, 0x280000
	v_add_co_u32_e32 v150, vcc, s26, v192
	s_mov_b64 s[26:27], 0x282000
	s_nop 0
	v_addc_co_u32_e32 v151, vcc, 0, v193, vcc
	v_lshl_add_u64 v[210:211], v[192:193], 0, s[26:27]
	s_mov_b32 s26, 0x282000
	v_add_co_u32_e32 v152, vcc, s26, v192
	v_and_b32_e32 v225, 0xffff0000, v228
	v_add_f32_e32 v3, 1.0, v3
	v_addc_co_u32_e32 v153, vcc, 0, v193, vcc
	global_load_dwordx4 v[162:165], v[150:151], off
	global_load_dwordx4 v[158:161], v[152:153], off
	v_lshlrev_b32_e32 v247, 16, v231
	v_and_b32_e32 v251, 0xffff0000, v231
	s_waitcnt vmcnt(4)
; __device__ __forceinline__ void unpack8(const u32x4 w, float (&v)[8]) { v[0] = bf_lo(w.x); v[1] = bf_hi(w.x); v[2] = bf_lo(w.y); v[3] = bf_hi(w.y); v[4] = bf_lo(w.z); v[5] = bf_hi(w.z); v[6] = bf_lo(w.w); v[7] = bf_hi(w.w); }
;     __device__ __forceinline__ void after(int te, f32x4 (&acc)[2][2][4][2], const Unit& u, int wr, int wc, int fr, int fq) const {
;     ...
;             for (int bj = 0; bj < 2; ++bj) { const int c = col0 + bj * HALF;
;                 const f32x4 s0 = *(const f32x4*)(gb + c), s1 = *(const f32x4*)(gb + c + 4), a0 = *(const f32x4*)(gb + D_MODEL + c), a1 = *(const f32x4*)(gb + D_MODEL + c + 4);
; #pragma unroll
;                 for (int ai = 0; ai < 2; ++ai) {
;                     u32x4 gs[4], ga[4];
; #pragma unroll
;                     for (int m = 0; m < 4; ++m) { const size_t r = (size_t)(row0 + ai * HALF + m * 16); gs[m] = *(const u32x4*)(proj + r * LDP + PGS + c); ga[m] = *(const u32x4*)(proj + r * LDP + PGA + c); }
; #pragma unroll
;                     for (int m = 0; m < 4; ++m) { float vs[8], va[8]; unpack8(gs[m], vs); unpack8(ga[m], va);
; #pragma unroll
;                         for (int e = 0; e < 4; ++e) {
;                             acc[ai][bj][m][0][e] *= (1.f + __expf(-(va[e] + a0[e]))) * __builtin_amdgcn_rcpf(1.f + __expf(-(vs[e] + s0[e])));
;                             acc[ai][bj][m][1][e] *= (1.f + __expf(-(va[4 + e] + a1[e]))) * __builtin_amdgcn_rcpf(1.f + __expf(-(vs[4 + e] + s1[e]))); } }
	v_lshlrev_b32_e32 v228, 16, v232
	v_and_b32_e32 v231, 0xffff0000, v232
	v_lshlrev_b32_e32 v248, 16, v233
	v_and_b32_e32 v249, 0xffff0000, v233
	v_lshlrev_b32_e32 v232, 16, v234
	v_and_b32_e32 v233, 0xffff0000, v234
	v_rcp_f32_e32 v234, v3
	v_add_f32_e32 v3, v143, v225
	v_mul_f32_e32 v3, 0xbfb8aa3b, v3
	v_exp_f32_e32 v3, v3
	v_add_f32_e32 v225, v147, v231
	v_lshlrev_b32_e32 v250, 16, v235
	v_and_b32_e32 v253, 0xffff0000, v235
	v_add_f32_e32 v3, 1.0, v3
	v_rcp_f32_e32 v231, v3
	v_add_f32_e32 v3, v127, v246
	v_mul_f32_e32 v3, 0xbfb8aa3b, v3
	v_exp_f32_e32 v3, v3
	v_add_f32_e32 v229, v130, v232
	v_mul_f32_e32 v229, 0xbfb8aa3b, v229
	v_mul_f32_e32 v225, 0xbfb8aa3b, v225
	v_add_f32_e32 v3, 1.0, v3
	v_rcp_f32_e32 v235, v3
	v_add_f32_e32 v3, v144, v227
	v_mul_f32_e32 v3, 0xbfb8aa3b, v3
	v_exp_f32_e32 v3, v3
	v_exp_f32_e32 v232, v229
	v_exp_f32_e32 v229, v225
	v_add_f32_e32 v225, v131, v233
	v_mul_f32_e32 v225, 0xbfb8aa3b, v225
	v_exp_f32_e32 v233, v225
	v_add_f32_e32 v225, v148, v248
	v_mul_f32_e32 v225, 0xbfb8aa3b, v225
	v_add_f32_e32 v3, 1.0, v3
	v_exp_f32_e32 v246, v225
	v_rcp_f32_e32 v248, v3
	v_add_f32_e32 v3, v128, v247
	v_add_f32_e32 v225, v132, v250
	v_mul_f32_e32 v3, 0xbfb8aa3b, v3
	v_mul_f32_e32 v225, 0xbfb8aa3b, v225
	v_add_f32_e32 v227, v145, v245
	v_exp_f32_e32 v3, v3
	v_exp_f32_e32 v250, v225
	v_add_f32_e32 v225, v149, v249
	v_mul_f32_e32 v227, 0xbfb8aa3b, v227
	v_exp_f32_e32 v227, v227
	v_mul_f32_e32 v225, 0xbfb8aa3b, v225
	v_exp_f32_e32 v247, v225
	v_add_f32_e32 v225, v129, v251
	v_mul_f32_e32 v225, 0xbfb8aa3b, v225
	v_add_f32_e32 v3, 1.0, v3
	v_exp_f32_e32 v225, v225
	v_rcp_f32_e32 v252, v3
	v_add_f32_e32 v3, 1.0, v227
	v_add_f32_e32 v228, v146, v228
	v_rcp_f32_e32 v249, v3
	v_add_f32_e32 v3, v133, v253
	v_mul_f32_e32 v228, 0xbfb8aa3b, v228
	v_mul_f32_e32 v3, 0xbfb8aa3b, v3
	v_exp_f32_e32 v228, v228
	v_exp_f32_e32 v251, v3
	v_add_f32_e32 v3, 1.0, v225
	v_rcp_f32_e32 v253, v3
	s_waitcnt vmcnt(3)
	v_lshlrev_b32_e32 v3, 16, v236
	v_add_f32_e32 v3, v142, v3
	v_mul_f32_e32 v3, 0xbfb8aa3b, v3
	v_pk_add_f32 v[228:229], v[228:229], 1.0 op_sel_hi:[1,0]
	v_exp_f32_e32 v3, v3
	v_pk_add_f32 v[246:247], v[246:247], 1.0 op_sel_hi:[1,0]
	v_pk_mul_f32 v[228:229], v[228:229], v[230:231]
	v_pk_mul_f32 v[230:231], v[246:247], v[248:249]
	v_pk_mul_f32 v[98:99], v[98:99], v[228:229]
	v_pk_add_f32 v[228:229], v[250:251], 1.0 op_sel_hi:[1,0]
	v_pk_mul_f32 v[100:101], v[100:101], v[230:231]
	v_pk_add_f32 v[230:231], v[232:233], 1.0 op_sel_hi:[1,0]
	v_pk_mul_f32 v[228:229], v[228:229], v[252:253]
	v_pk_mul_f32 v[230:231], v[230:231], v[234:235]
	v_pk_mul_f32 v[96:97], v[96:97], v[228:229]
	v_lshlrev_b32_e32 v229, 16, v238
	v_add_f32_e32 v3, 1.0, v3
	v_pk_mul_f32 v[94:95], v[94:95], v[230:231]
	v_rcp_f32_e32 v230, v3
	v_add_f32_e32 v3, v126, v229
	v_mul_f32_e32 v3, 0xbfb8aa3b, v3
	v_exp_f32_e32 v3, v3
	v_and_b32_e32 v225, 0xffff0000, v236
	s_mov_b64 s[26:27], 0x2c0000
	v_lshl_add_u64 v[212:213], v[192:193], 0, s[26:27]
	v_add_f32_e32 v3, 1.0, v3
	v_rcp_f32_e32 v234, v3
	v_add_f32_e32 v3, v143, v225
	v_mul_f32_e32 v3, 0xbfb8aa3b, v3
	v_exp_f32_e32 v3, v3
	s_mov_b32 s26, 0x2c0000
	v_add_co_u32_e32 v150, vcc, s26, v192
	s_mov_b64 s[26:27], 0x2c2000
	s_nop 0
	v_addc_co_u32_e32 v151, vcc, 0, v193, vcc
	v_lshl_add_u64 v[214:215], v[192:193], 0, s[26:27]
	s_mov_b32 s26, 0x2c2000
	v_and_b32_e32 v233, 0xffff0000, v238
	s_waitcnt vmcnt(2)
	v_and_b32_e32 v231, 0xffff0000, v240
	v_add_f32_e32 v3, 1.0, v3
	v_add_co_u32_e32 v152, vcc, s26, v192
	v_add_f32_e32 v225, v147, v231
	v_rcp_f32_e32 v231, v3
	v_add_f32_e32 v3, v127, v233
	v_addc_co_u32_e32 v153, vcc, 0, v193, vcc
	v_mul_f32_e32 v3, 0xbfb8aa3b, v3
	global_load_dwordx4 v[154:157], v[150:151], off
	s_nop 0
	global_load_dwordx4 v[150:153], v[152:153], off
	v_exp_f32_e32 v3, v3
	v_lshlrev_b32_e32 v232, 16, v242
	v_add_f32_e32 v229, v130, v232
	v_lshlrev_b32_e32 v227, 16, v237
	v_and_b32_e32 v235, 0xffff0000, v242
	v_mul_f32_e32 v229, 0xbfb8aa3b, v229
	v_mul_f32_e32 v225, 0xbfb8aa3b, v225
	v_add_f32_e32 v3, 1.0, v3
	v_exp_f32_e32 v232, v229
	v_exp_f32_e32 v229, v225
	v_add_f32_e32 v225, v131, v235
	v_rcp_f32_e32 v235, v3
	v_add_f32_e32 v3, v144, v227
	v_mul_f32_e32 v3, 0xbfb8aa3b, v3
	v_exp_f32_e32 v3, v3
	v_lshlrev_b32_e32 v236, 16, v241
	v_mul_f32_e32 v225, 0xbfb8aa3b, v225
	v_exp_f32_e32 v233, v225
	v_add_f32_e32 v225, v148, v236
	v_lshlrev_b32_e32 v245, 16, v239
	v_lshlrev_b32_e32 v228, 16, v240
	v_lshlrev_b32_e32 v240, 16, v243
	v_mul_f32_e32 v225, 0xbfb8aa3b, v225
	v_add_f32_e32 v3, 1.0, v3
	v_and_b32_e32 v237, 0xffff0000, v237
	v_exp_f32_e32 v236, v225
	v_rcp_f32_e32 v238, v3
	v_add_f32_e32 v3, v128, v245
	v_add_f32_e32 v225, v132, v240
	v_and_b32_e32 v246, 0xffff0000, v239
	v_and_b32_e32 v239, 0xffff0000, v241
	v_mul_f32_e32 v3, 0xbfb8aa3b, v3
	v_mul_f32_e32 v225, 0xbfb8aa3b, v225
	v_add_f32_e32 v227, v145, v237
	v_exp_f32_e32 v3, v3
	v_exp_f32_e32 v240, v225
	v_add_f32_e32 v225, v149, v239
	v_mul_f32_e32 v227, 0xbfb8aa3b, v227
	v_exp_f32_e32 v227, v227
	v_mul_f32_e32 v225, 0xbfb8aa3b, v225
	v_exp_f32_e32 v237, v225
	v_add_f32_e32 v225, v129, v246
	v_mul_f32_e32 v225, 0xbfb8aa3b, v225
	v_add_f32_e32 v3, 1.0, v3
	v_exp_f32_e32 v225, v225
	v_and_b32_e32 v241, 0xffff0000, v243
	v_rcp_f32_e32 v242, v3
	v_add_f32_e32 v3, 1.0, v227
	v_rcp_f32_e32 v239, v3
	v_add_f32_e32 v3, v133, v241
	v_add_f32_e32 v228, v146, v228
	v_mul_f32_e32 v3, 0xbfb8aa3b, v3
	v_mul_f32_e32 v228, 0xbfb8aa3b, v228
	v_exp_f32_e32 v241, v3
	v_add_f32_e32 v3, 1.0, v225
	v_exp_f32_e32 v228, v228
	v_rcp_f32_e32 v243, v3
	s_waitcnt vmcnt(3)
; __device__ __forceinline__ void unpack8(const u32x4 w, float (&v)[8]) { v[0] = bf_lo(w.x); v[1] = bf_hi(w.x); v[2] = bf_lo(w.y); v[3] = bf_hi(w.y); v[4] = bf_lo(w.z); v[5] = bf_hi(w.z); v[6] = bf_lo(w.w); v[7] = bf_hi(w.w); }
;     __device__ __forceinline__ void after(int te, f32x4 (&acc)[2][2][4][2], const Unit& u, int wr, int wc, int fr, int fq) const {
;     ...
;             for (int bj = 0; bj < 2; ++bj) { const int c = col0 + bj * HALF;
;                 const f32x4 s0 = *(const f32x4*)(gb + c), s1 = *(const f32x4*)(gb + c + 4), a0 = *(const f32x4*)(gb + D_MODEL + c), a1 = *(const f32x4*)(gb + D_MODEL + c + 4);
; #pragma unroll
;                 for (int ai = 0; ai < 2; ++ai) {
;                     u32x4 gs[4], ga[4];
; #pragma unroll
;                     for (int m = 0; m < 4; ++m) { const size_t r = (size_t)(row0 + ai * HALF + m * 16); gs[m] = *(const u32x4*)(proj + r * LDP + PGS + c); ga[m] = *(const u32x4*)(proj + r * LDP + PGA + c); }
; #pragma unroll
;                     for (int m = 0; m < 4; ++m) { float vs[8], va[8]; unpack8(gs[m], vs); unpack8(ga[m], va);
; #pragma unroll
;                         for (int e = 0; e < 4; ++e) {
;                             acc[ai][bj][m][0][e] *= (1.f + __expf(-(va[e] + a0[e]))) * __builtin_amdgcn_rcpf(1.f + __expf(-(vs[e] + s0[e])));
;                             acc[ai][bj][m][1][e] *= (1.f + __expf(-(va[4 + e] + a1[e]))) * __builtin_amdgcn_rcpf(1.f + __expf(-(vs[4 + e] + s1[e]))); } }
	v_lshlrev_b32_e32 v3, 16, v162
	v_add_f32_e32 v3, v142, v3
	v_mul_f32_e32 v3, 0xbfb8aa3b, v3
	v_exp_f32_e32 v3, v3
	v_pk_add_f32 v[236:237], v[236:237], 1.0 op_sel_hi:[1,0]
	v_pk_add_f32 v[228:229], v[228:229], 1.0 op_sel_hi:[1,0]
	v_and_b32_e32 v225, 0xffff0000, v162
	v_pk_mul_f32 v[228:229], v[228:229], v[230:231]
	v_pk_mul_f32 v[230:231], v[236:237], v[238:239]
	v_pk_mul_f32 v[90:91], v[90:91], v[228:229]
	v_pk_mul_f32 v[92:93], v[92:93], v[230:231]
	v_pk_add_f32 v[228:229], v[240:241], 1.0 op_sel_hi:[1,0]
	v_pk_add_f32 v[230:231], v[232:233], 1.0 op_sel_hi:[1,0]
	v_pk_mul_f32 v[228:229], v[228:229], v[242:243]
	v_pk_mul_f32 v[230:231], v[230:231], v[234:235]
	v_lshlrev_b32_e32 v162, 16, v164
	v_add_f32_e32 v3, 1.0, v3
	v_pk_mul_f32 v[88:89], v[88:89], v[228:229]
	v_pk_mul_f32 v[86:87], v[86:87], v[230:231]
	s_waitcnt vmcnt(2)
	v_lshlrev_b32_e32 v228, 16, v159
	v_and_b32_e32 v234, 0xffff0000, v159
	v_lshlrev_b32_e32 v159, 16, v160
	v_and_b32_e32 v230, 0xffff0000, v160
	v_rcp_f32_e32 v160, v3
	v_add_f32_e32 v3, v126, v162
	v_mul_f32_e32 v3, 0xbfb8aa3b, v3
	v_exp_f32_e32 v3, v3
	v_lshlrev_b32_e32 v227, 16, v163
	v_and_b32_e32 v229, 0xffff0000, v163
	v_and_b32_e32 v163, 0xffff0000, v164
	v_lshlrev_b32_e32 v164, 16, v158
	v_add_f32_e32 v3, 1.0, v3
	v_lshlrev_b32_e32 v231, 16, v165
	v_and_b32_e32 v233, 0xffff0000, v165
	v_and_b32_e32 v165, 0xffff0000, v158
	v_add_f32_e32 v158, v146, v164
	v_rcp_f32_e32 v164, v3
	v_add_f32_e32 v3, v143, v225
	v_mul_f32_e32 v3, 0xbfb8aa3b, v3
	v_exp_f32_e32 v3, v3
	v_lshlrev_b32_e32 v232, 16, v161
	v_and_b32_e32 v235, 0xffff0000, v161
	v_add_f32_e32 v159, v130, v159
	v_add_f32_e32 v3, 1.0, v3
	v_rcp_f32_e32 v161, v3
	v_add_f32_e32 v3, v127, v163
	v_mul_f32_e32 v3, 0xbfb8aa3b, v3
	v_exp_f32_e32 v3, v3
	v_mul_f32_e32 v159, 0xbfb8aa3b, v159
	v_exp_f32_e32 v162, v159
	v_add_f32_e32 v159, v147, v165
	v_add_f32_e32 v3, 1.0, v3
	v_rcp_f32_e32 v165, v3
	v_add_f32_e32 v3, v144, v227
	v_mul_f32_e32 v3, 0xbfb8aa3b, v3
	v_exp_f32_e32 v3, v3
	v_add_f32_e32 v163, v131, v230
	v_add_f32_e32 v225, v148, v228
	v_add_f32_e32 v227, v145, v229
	v_add_f32_e32 v3, 1.0, v3
	v_rcp_f32_e32 v230, v3
	v_add_f32_e32 v3, v128, v231
	v_mul_f32_e32 v3, 0xbfb8aa3b, v3
	v_mul_f32_e32 v225, 0xbfb8aa3b, v225
	v_exp_f32_e32 v3, v3
	v_mul_f32_e32 v227, 0xbfb8aa3b, v227
	v_exp_f32_e32 v228, v225
	v_add_f32_e32 v225, v132, v232
	v_exp_f32_e32 v227, v227
	v_mul_f32_e32 v225, 0xbfb8aa3b, v225
	v_exp_f32_e32 v232, v225
	v_add_f32_e32 v225, v149, v234
	v_mul_f32_e32 v158, 0xbfb8aa3b, v158
	v_mul_f32_e32 v159, 0xbfb8aa3b, v159
	v_add_f32_e32 v3, 1.0, v3
	v_mul_f32_e32 v225, 0xbfb8aa3b, v225
	v_exp_f32_e32 v158, v158
	v_exp_f32_e32 v159, v159
	v_exp_f32_e32 v229, v225
	v_rcp_f32_e32 v234, v3
	v_add_f32_e32 v3, 1.0, v227
	v_rcp_f32_e32 v231, v3
	v_pk_add_f32 v[228:229], v[228:229], 1.0 op_sel_hi:[1,0]
	v_pk_add_f32 v[158:159], v[158:159], 1.0 op_sel_hi:[1,0]
	v_add_f32_e32 v3, v133, v235
	v_pk_mul_f32 v[158:159], v[158:159], v[160:161]
	v_pk_mul_f32 v[160:161], v[228:229], v[230:231]
	v_mul_f32_e32 v3, 0xbfb8aa3b, v3
	v_pk_mul_f32 v[84:85], v[84:85], v[160:161]
	v_add_f32_e32 v160, v129, v233
	v_mul_f32_e32 v160, 0xbfb8aa3b, v160
	v_exp_f32_e32 v160, v160
	v_exp_f32_e32 v233, v3
	s_waitcnt vmcnt(1)
	v_lshlrev_b32_e32 v225, 16, v155
	v_and_b32_e32 v227, 0xffff0000, v155
	v_add_f32_e32 v3, 1.0, v160
	v_rcp_f32_e32 v235, v3
	v_lshlrev_b32_e32 v3, 16, v154
	v_add_f32_e32 v3, v142, v3
	v_mul_f32_e32 v3, 0xbfb8aa3b, v3
	v_exp_f32_e32 v3, v3
	v_lshlrev_b32_e32 v155, 16, v156
	v_and_b32_e32 v236, 0xffff0000, v156
	s_waitcnt vmcnt(0)
	v_lshlrev_b32_e32 v156, 16, v150
	v_add_f32_e32 v3, 1.0, v3
	v_mul_f32_e32 v163, 0xbfb8aa3b, v163
	v_add_f32_e32 v142, v146, v156
	v_rcp_f32_e32 v146, v3
	v_add_f32_e32 v3, v126, v155
	v_exp_f32_e32 v163, v163
	v_mul_f32_e32 v3, 0xbfb8aa3b, v3
	v_exp_f32_e32 v3, v3
	v_pk_mul_f32 v[82:83], v[82:83], v[158:159]
	v_pk_add_f32 v[158:159], v[232:233], 1.0 op_sel_hi:[1,0]
	v_pk_add_f32 v[160:161], v[162:163], 1.0 op_sel_hi:[1,0]
	v_pk_mul_f32 v[158:159], v[158:159], v[234:235]
	v_pk_mul_f32 v[160:161], v[160:161], v[164:165]
	v_and_b32_e32 v150, 0xffff0000, v150
	v_lshlrev_b32_e32 v239, 16, v151
	v_and_b32_e32 v240, 0xffff0000, v151
	v_lshlrev_b32_e32 v151, 16, v152
	global_load_dwordx4 v[228:231], v[192:193], off offset:256
	global_load_dwordx4 v[232:235], v[202:203], off offset:256
	v_add_f32_e32 v3, 1.0, v3
	v_pk_mul_f32 v[80:81], v[80:81], v[158:159]
	v_pk_mul_f32 v[78:79], v[78:79], v[160:161]
	v_and_b32_e32 v241, 0xffff0000, v152
	v_lshlrev_b32_e32 v242, 16, v153
	v_and_b32_e32 v243, 0xffff0000, v153
	v_add_f32_e32 v126, v130, v151
	v_rcp_f32_e32 v130, v3
	v_add_f32_e32 v3, v147, v150
	global_load_dwordx4 v[150:153], v[196:197], off offset:528
	global_load_dwordx4 v[158:161], v[196:197], off offset:512
	v_and_b32_e32 v154, 0xffff0000, v154
	v_lshlrev_b32_e32 v237, 16, v157
	v_and_b32_e32 v238, 0xffff0000, v157
	v_add_f32_e32 v143, v143, v154
	global_load_dwordx4 v[154:157], v[198:199], off offset:528
	global_load_dwordx4 v[162:165], v[198:199], off offset:512
	v_mul_f32_e32 v143, 0xbfb8aa3b, v143
	v_exp_f32_e32 v147, v143
	v_mul_f32_e32 v3, 0xbfb8aa3b, v3
	v_exp_f32_e32 v143, v3
	v_add_f32_e32 v145, v145, v227
	v_add_f32_e32 v3, 1.0, v147
	v_rcp_f32_e32 v147, v3
	v_add_f32_e32 v3, v127, v236
	v_mul_f32_e32 v3, 0xbfb8aa3b, v3
	v_exp_f32_e32 v3, v3
	v_add_f32_e32 v127, v131, v241
	v_mul_f32_e32 v145, 0xbfb8aa3b, v145
	v_add_f32_e32 v129, v129, v238
	v_add_f32_e32 v3, 1.0, v3
	v_rcp_f32_e32 v131, v3
	v_add_f32_e32 v3, v144, v225
	v_mul_f32_e32 v3, 0xbfb8aa3b, v3
	v_exp_f32_e32 v3, v3
	v_add_f32_e32 v144, v148, v239
; __device__ __forceinline__ void unpack8(const u32x4 w, float (&v)[8]) { v[0] = bf_lo(w.x); v[1] = bf_hi(w.x); v[2] = bf_lo(w.y); v[3] = bf_hi(w.y); v[4] = bf_lo(w.z); v[5] = bf_hi(w.z); v[6] = bf_lo(w.w); v[7] = bf_hi(w.w); }
;     __device__ __forceinline__ void after(int te, f32x4 (&acc)[2][2][4][2], const Unit& u, int wr, int wc, int fr, int fq) const {
;     ...
;             for (int bj = 0; bj < 2; ++bj) { const int c = col0 + bj * HALF;
;                 const f32x4 s0 = *(const f32x4*)(gb + c), s1 = *(const f32x4*)(gb + c + 4), a0 = *(const f32x4*)(gb + D_MODEL + c), a1 = *(const f32x4*)(gb + D_MODEL + c + 4);
; #pragma unroll
;                 for (int ai = 0; ai < 2; ++ai) {
;                     u32x4 gs[4], ga[4];
; #pragma unroll
;                     for (int m = 0; m < 4; ++m) { const size_t r = (size_t)(row0 + ai * HALF + m * 16); gs[m] = *(const u32x4*)(proj + r * LDP + PGS + c); ga[m] = *(const u32x4*)(proj + r * LDP + PGA + c); }
; #pragma unroll
;                     for (int m = 0; m < 4; ++m) { float vs[8], va[8]; unpack8(gs[m], vs); unpack8(ga[m], va);
; #pragma unroll
;                         for (int e = 0; e < 4; ++e) {
;                             acc[ai][bj][m][0][e] *= (1.f + __expf(-(va[e] + a0[e]))) * __builtin_amdgcn_rcpf(1.f + __expf(-(vs[e] + s0[e])));
;                             acc[ai][bj][m][1][e] *= (1.f + __expf(-(va[4 + e] + a1[e]))) * __builtin_amdgcn_rcpf(1.f + __expf(-(vs[4 + e] + s1[e]))); } }
	v_mul_f32_e32 v129, 0xbfb8aa3b, v129
	v_mul_f32_e32 v142, 0xbfb8aa3b, v142
	v_add_f32_e32 v3, 1.0, v3
	v_rcp_f32_e32 v148, v3
	v_add_f32_e32 v3, v128, v237
	v_mul_f32_e32 v3, 0xbfb8aa3b, v3
	v_exp_f32_e32 v3, v3
	v_add_f32_e32 v128, v132, v242
	v_add_f32_e32 v132, v149, v240
	v_exp_f32_e32 v149, v145
	v_add_f32_e32 v3, 1.0, v3
	v_mul_f32_e32 v132, 0xbfb8aa3b, v132
	v_exp_f32_e32 v145, v132
	v_rcp_f32_e32 v132, v3
	v_add_f32_e32 v3, 1.0, v149
	v_rcp_f32_e32 v149, v3
	v_add_f32_e32 v3, v133, v243
	v_exp_f32_e32 v133, v129
	v_mul_f32_e32 v126, 0xbfb8aa3b, v126
	v_mul_f32_e32 v127, 0xbfb8aa3b, v127
	v_mul_f32_e32 v144, 0xbfb8aa3b, v144
	v_mul_f32_e32 v128, 0xbfb8aa3b, v128
	v_mul_f32_e32 v3, 0xbfb8aa3b, v3
	v_exp_f32_e32 v142, v142
	v_exp_f32_e32 v126, v126
	v_exp_f32_e32 v127, v127
	v_exp_f32_e32 v144, v144
	v_exp_f32_e32 v128, v128
	v_exp_f32_e32 v129, v3
	v_add_f32_e32 v3, 1.0, v133
	v_rcp_f32_e32 v133, v3
	v_pk_add_f32 v[144:145], v[144:145], 1.0 op_sel_hi:[1,0]
	v_pk_add_f32 v[142:143], v[142:143], 1.0 op_sel_hi:[1,0]
	v_pk_add_f32 v[128:129], v[128:129], 1.0 op_sel_hi:[1,0]
	v_pk_add_f32 v[126:127], v[126:127], 1.0 op_sel_hi:[1,0]
	v_pk_mul_f32 v[142:143], v[142:143], v[146:147]
	v_pk_mul_f32 v[144:145], v[144:145], v[148:149]
	v_pk_mul_f32 v[126:127], v[126:127], v[130:131]
	v_pk_mul_f32 v[128:129], v[128:129], v[132:133]
	v_pk_mul_f32 v[76:77], v[76:77], v[144:145]
	v_pk_mul_f32 v[74:75], v[74:75], v[142:143]
	v_pk_mul_f32 v[72:73], v[72:73], v[128:129]
	v_pk_mul_f32 v[70:71], v[70:71], v[126:127]
	global_load_dwordx4 v[196:199], v[4:5], off offset:256
	global_load_dwordx4 v[236:239], v[186:187], off offset:256
	global_load_dwordx4 v[146:149], v[188:189], off offset:256
	global_load_dwordx4 v[142:145], v[190:191], off offset:256
	global_load_dwordx4 v[130:133], v[194:195], off offset:256
	global_load_dwordx4 v[126:129], v[200:201], off offset:256
	s_waitcnt vmcnt(11)
	v_lshlrev_b32_e32 v3, 16, v228
	v_lshlrev_b32_e32 v187, 16, v230
	v_and_b32_e32 v5, 0xffff0000, v228
	s_waitcnt vmcnt(10)
	v_lshlrev_b32_e32 v188, 16, v234
	v_and_b32_e32 v189, 0xffff0000, v230
	v_lshlrev_b32_e32 v192, 16, v229
	v_and_b32_e32 v191, 0xffff0000, v232
	v_lshlrev_b32_e32 v195, 16, v231
	v_lshlrev_b32_e32 v194, 16, v233
	v_and_b32_e32 v193, 0xffff0000, v229
	v_lshlrev_b32_e32 v203, 16, v235
	s_waitcnt vmcnt(8)
	v_add_f32_e32 v3, v158, v3
	v_mul_f32_e32 v3, 0xbfb8aa3b, v3
	v_exp_f32_e32 v3, v3
	v_add_f32_e32 v193, v161, v193
	v_mul_f32_e32 v193, 0xbfb8aa3b, v193
	v_lshlrev_b32_e32 v4, 16, v232
	v_add_f32_e32 v3, 1.0, v3
	v_rcp_f32_e32 v186, v3
	v_add_f32_e32 v3, v150, v187
	v_mul_f32_e32 v3, 0xbfb8aa3b, v3
	v_exp_f32_e32 v3, v3
	s_waitcnt vmcnt(7)
	v_add_f32_e32 v187, v154, v188
	v_mul_f32_e32 v187, 0xbfb8aa3b, v187
	v_exp_f32_e32 v188, v187
	v_add_f32_e32 v3, 1.0, v3
	v_rcp_f32_e32 v190, v3
	v_add_f32_e32 v3, v159, v5
	v_mul_f32_e32 v3, 0xbfb8aa3b, v3
	v_exp_f32_e32 v3, v3
	s_waitcnt vmcnt(6)
	v_add_f32_e32 v5, v163, v191
	v_and_b32_e32 v202, 0xffff0000, v233
	v_and_b32_e32 v200, 0xffff0000, v234
	v_add_f32_e32 v3, 1.0, v3
	v_rcp_f32_e32 v187, v3
	v_add_f32_e32 v3, v151, v189
	v_mul_f32_e32 v3, 0xbfb8aa3b, v3
	v_exp_f32_e32 v3, v3
	v_add_f32_e32 v4, v162, v4
	v_add_f32_e32 v189, v155, v200
	v_mul_f32_e32 v4, 0xbfb8aa3b, v4
	v_add_f32_e32 v3, 1.0, v3
	v_rcp_f32_e32 v191, v3
	v_add_f32_e32 v3, v160, v192
	v_mul_f32_e32 v3, 0xbfb8aa3b, v3
	v_exp_f32_e32 v3, v3
	v_add_f32_e32 v192, v164, v194
	v_mul_f32_e32 v5, 0xbfb8aa3b, v5
	v_mul_f32_e32 v192, 0xbfb8aa3b, v192
	v_add_f32_e32 v3, 1.0, v3
	v_rcp_f32_e32 v194, v3
	v_add_f32_e32 v3, v152, v195
	v_mul_f32_e32 v3, 0xbfb8aa3b, v3
	v_exp_f32_e32 v3, v3
	v_add_f32_e32 v195, v156, v203
	v_exp_f32_e32 v203, v193
	v_mul_f32_e32 v195, 0xbfb8aa3b, v195
	v_exp_f32_e32 v200, v195
	v_add_f32_e32 v195, v165, v202
	v_add_f32_e32 v3, 1.0, v3
	v_mul_f32_e32 v193, 0xbfb8aa3b, v195
	v_exp_f32_e32 v4, v4
	v_exp_f32_e32 v5, v5
	v_exp_f32_e32 v192, v192
	v_exp_f32_e32 v193, v193
	v_rcp_f32_e32 v202, v3
	v_add_f32_e32 v3, 1.0, v203
	v_rcp_f32_e32 v195, v3
	v_pk_add_f32 v[192:193], v[192:193], 1.0 op_sel_hi:[1,0]
	v_pk_add_f32 v[4:5], v[4:5], 1.0 op_sel_hi:[1,0]
	v_and_b32_e32 v201, 0xffff0000, v231
	v_pk_mul_f32 v[4:5], v[4:5], v[186:187]
	v_pk_mul_f32 v[186:187], v[192:193], v[194:195]
	v_and_b32_e32 v225, 0xffff0000, v235
	v_pk_mul_f32 v[68:69], v[68:69], v[186:187]
	v_add_f32_e32 v186, v153, v201
	v_mul_f32_e32 v186, 0xbfb8aa3b, v186
	v_exp_f32_e32 v186, v186
	v_add_f32_e32 v3, v157, v225
	v_mul_f32_e32 v3, 0xbfb8aa3b, v3
	v_exp_f32_e32 v201, v3
	v_add_f32_e32 v3, 1.0, v186
	v_mul_f32_e32 v189, 0xbfb8aa3b, v189
	v_rcp_f32_e32 v203, v3
	s_waitcnt vmcnt(5)
	v_lshlrev_b32_e32 v3, 16, v196
	v_exp_f32_e32 v189, v189
	v_add_f32_e32 v3, v158, v3
	v_mul_f32_e32 v3, 0xbfb8aa3b, v3
	v_exp_f32_e32 v3, v3
	v_pk_add_f32 v[186:187], v[188:189], 1.0 op_sel_hi:[1,0]
	v_pk_mul_f32 v[66:67], v[66:67], v[4:5]
	v_pk_mul_f32 v[186:187], v[186:187], v[190:191]
	v_add_f32_e32 v3, 1.0, v3
	v_pk_mul_f32 v[62:63], v[62:63], v[186:187]
	v_lshlrev_b32_e32 v187, 16, v198
	v_rcp_f32_e32 v186, v3
	v_add_f32_e32 v3, v150, v187
	v_mul_f32_e32 v3, 0xbfb8aa3b, v3
	v_exp_f32_e32 v3, v3
	v_pk_add_f32 v[4:5], v[200:201], 1.0 op_sel_hi:[1,0]
	s_waitcnt vmcnt(4)
; __device__ __forceinline__ void unpack8(const u32x4 w, float (&v)[8]) { v[0] = bf_lo(w.x); v[1] = bf_hi(w.x); v[2] = bf_lo(w.y); v[3] = bf_hi(w.y); v[4] = bf_lo(w.z); v[5] = bf_hi(w.z); v[6] = bf_lo(w.w); v[7] = bf_hi(w.w); }
;     __device__ __forceinline__ void after(int te, f32x4 (&acc)[2][2][4][2], const Unit& u, int wr, int wc, int fr, int fq) const {
;     ...
;             for (int bj = 0; bj < 2; ++bj) { const int c = col0 + bj * HALF;
;                 const f32x4 s0 = *(const f32x4*)(gb + c), s1 = *(const f32x4*)(gb + c + 4), a0 = *(const f32x4*)(gb + D_MODEL + c), a1 = *(const f32x4*)(gb + D_MODEL + c + 4);
; #pragma unroll
;                 for (int ai = 0; ai < 2; ++ai) {
;                     u32x4 gs[4], ga[4];
; #pragma unroll
;                     for (int m = 0; m < 4; ++m) { const size_t r = (size_t)(row0 + ai * HALF + m * 16); gs[m] = *(const u32x4*)(proj + r * LDP + PGS + c); ga[m] = *(const u32x4*)(proj + r * LDP + PGA + c); }
; #pragma unroll
;                     for (int m = 0; m < 4; ++m) { float vs[8], va[8]; unpack8(gs[m], vs); unpack8(ga[m], va);
; #pragma unroll
;                         for (int e = 0; e < 4; ++e) {
;                             acc[ai][bj][m][0][e] *= (1.f + __expf(-(va[e] + a0[e]))) * __builtin_amdgcn_rcpf(1.f + __expf(-(vs[e] + s0[e])));
;                             acc[ai][bj][m][1][e] *= (1.f + __expf(-(va[4 + e] + a1[e]))) * __builtin_amdgcn_rcpf(1.f + __expf(-(vs[4 + e] + s1[e]))); } }
	v_lshlrev_b32_e32 v188, 16, v238
	v_pk_mul_f32 v[4:5], v[4:5], v[202:203]
	v_add_f32_e32 v3, 1.0, v3
	v_pk_mul_f32 v[64:65], v[64:65], v[4:5]
	v_and_b32_e32 v5, 0xffff0000, v196
	v_rcp_f32_e32 v190, v3
	v_add_f32_e32 v3, v159, v5
	v_mul_f32_e32 v3, 0xbfb8aa3b, v3
	v_exp_f32_e32 v3, v3
	v_add_f32_e32 v187, v154, v188
	v_and_b32_e32 v189, 0xffff0000, v198
	v_mul_f32_e32 v187, 0xbfb8aa3b, v187
	v_add_f32_e32 v3, 1.0, v3
	v_exp_f32_e32 v188, v187
	v_rcp_f32_e32 v187, v3
	v_add_f32_e32 v3, v151, v189
	v_mul_f32_e32 v3, 0xbfb8aa3b, v3
	v_exp_f32_e32 v3, v3
	v_lshlrev_b32_e32 v192, 16, v197
	v_and_b32_e32 v191, 0xffff0000, v236
	v_add_f32_e32 v5, v163, v191
	v_add_f32_e32 v3, 1.0, v3
	v_rcp_f32_e32 v191, v3
	v_add_f32_e32 v3, v160, v192
	v_mul_f32_e32 v3, 0xbfb8aa3b, v3
	v_exp_f32_e32 v3, v3
	v_lshlrev_b32_e32 v195, 16, v199
	v_lshlrev_b32_e32 v194, 16, v237
	v_and_b32_e32 v193, 0xffff0000, v197
	v_add_f32_e32 v3, 1.0, v3
	v_add_f32_e32 v192, v164, v194
	v_rcp_f32_e32 v194, v3
	v_add_f32_e32 v3, v152, v195
	v_mul_f32_e32 v3, 0xbfb8aa3b, v3
	v_add_f32_e32 v193, v161, v193
	v_and_b32_e32 v197, 0xffff0000, v199
	v_lshlrev_b32_e32 v199, 16, v239
	v_exp_f32_e32 v3, v3
	v_mul_f32_e32 v193, 0xbfb8aa3b, v193
	v_add_f32_e32 v195, v156, v199
	v_exp_f32_e32 v199, v193
	v_lshlrev_b32_e32 v4, 16, v236
	v_and_b32_e32 v198, 0xffff0000, v237
	v_and_b32_e32 v196, 0xffff0000, v238
	v_mul_f32_e32 v195, 0xbfb8aa3b, v195
	v_add_f32_e32 v4, v162, v4
	v_add_f32_e32 v189, v155, v196
	v_exp_f32_e32 v196, v195
	v_add_f32_e32 v195, v165, v198
	v_mul_f32_e32 v4, 0xbfb8aa3b, v4
	v_mul_f32_e32 v5, 0xbfb8aa3b, v5
	v_mul_f32_e32 v192, 0xbfb8aa3b, v192
	v_add_f32_e32 v3, 1.0, v3
	v_mul_f32_e32 v193, 0xbfb8aa3b, v195
	v_exp_f32_e32 v4, v4
	v_exp_f32_e32 v5, v5
	v_exp_f32_e32 v192, v192
	v_exp_f32_e32 v193, v193
	v_rcp_f32_e32 v198, v3
	v_add_f32_e32 v3, 1.0, v199
	v_rcp_f32_e32 v195, v3
	v_pk_add_f32 v[192:193], v[192:193], 1.0 op_sel_hi:[1,0]
	v_pk_add_f32 v[4:5], v[4:5], 1.0 op_sel_hi:[1,0]
	v_and_b32_e32 v200, 0xffff0000, v239
	v_pk_mul_f32 v[4:5], v[4:5], v[186:187]
	v_pk_mul_f32 v[186:187], v[192:193], v[194:195]
	v_add_f32_e32 v3, v157, v200
	v_pk_mul_f32 v[60:61], v[60:61], v[186:187]
	v_add_f32_e32 v186, v153, v197
	v_mul_f32_e32 v186, 0xbfb8aa3b, v186
	v_exp_f32_e32 v186, v186
	v_mul_f32_e32 v3, 0xbfb8aa3b, v3
	v_exp_f32_e32 v197, v3
	v_mul_f32_e32 v189, 0xbfb8aa3b, v189
	v_add_f32_e32 v3, 1.0, v186
	v_rcp_f32_e32 v199, v3
	s_waitcnt vmcnt(3)
	v_lshlrev_b32_e32 v3, 16, v146
	v_add_f32_e32 v3, v158, v3
	v_exp_f32_e32 v189, v189
	v_mul_f32_e32 v3, 0xbfb8aa3b, v3
	v_exp_f32_e32 v3, v3
	v_pk_mul_f32 v[58:59], v[58:59], v[4:5]
	v_pk_add_f32 v[4:5], v[196:197], 1.0 op_sel_hi:[1,0]
	v_pk_add_f32 v[186:187], v[188:189], 1.0 op_sel_hi:[1,0]
	v_pk_mul_f32 v[4:5], v[4:5], v[198:199]
	v_pk_mul_f32 v[186:187], v[186:187], v[190:191]
	v_pk_mul_f32 v[56:57], v[56:57], v[4:5]
	v_and_b32_e32 v5, 0xffff0000, v146
	v_lshlrev_b32_e32 v146, 16, v148
	v_add_f32_e32 v3, 1.0, v3
	v_pk_mul_f32 v[54:55], v[54:55], v[186:187]
	v_lshlrev_b32_e32 v186, 16, v147
	v_and_b32_e32 v187, 0xffff0000, v147
	v_and_b32_e32 v147, 0xffff0000, v148
	s_waitcnt vmcnt(2)
	v_lshlrev_b32_e32 v4, 16, v142
	v_and_b32_e32 v148, 0xffff0000, v142
	v_rcp_f32_e32 v142, v3
	v_add_f32_e32 v3, v150, v146
	v_mul_f32_e32 v3, 0xbfb8aa3b, v3
	v_exp_f32_e32 v3, v3
	v_lshlrev_b32_e32 v188, 16, v149
	v_and_b32_e32 v189, 0xffff0000, v149
	v_lshlrev_b32_e32 v149, 16, v143
	v_add_f32_e32 v3, 1.0, v3
	v_rcp_f32_e32 v146, v3
	v_add_f32_e32 v3, v159, v5
	v_mul_f32_e32 v3, 0xbfb8aa3b, v3
	v_exp_f32_e32 v3, v3
	v_and_b32_e32 v190, 0xffff0000, v143
	v_lshlrev_b32_e32 v143, 16, v144
	v_add_f32_e32 v143, v154, v143
	v_mul_f32_e32 v143, 0xbfb8aa3b, v143
	v_add_f32_e32 v3, 1.0, v3
	v_and_b32_e32 v191, 0xffff0000, v144
	v_exp_f32_e32 v144, v143
	v_rcp_f32_e32 v143, v3
	v_add_f32_e32 v3, v151, v147
	v_mul_f32_e32 v3, 0xbfb8aa3b, v3
	v_exp_f32_e32 v3, v3
	v_add_f32_e32 v187, v161, v187
	v_lshlrev_b32_e32 v192, 16, v145
	v_mul_f32_e32 v187, 0xbfb8aa3b, v187
	v_add_f32_e32 v3, 1.0, v3
	v_rcp_f32_e32 v147, v3
	v_add_f32_e32 v3, v160, v186
	v_mul_f32_e32 v3, 0xbfb8aa3b, v3
	v_exp_f32_e32 v3, v3
	v_add_f32_e32 v5, v163, v148
	v_add_f32_e32 v148, v164, v149
	v_add_f32_e32 v149, v156, v192
	v_add_f32_e32 v3, 1.0, v3
	v_rcp_f32_e32 v186, v3
	v_add_f32_e32 v3, v152, v188
	v_mul_f32_e32 v3, 0xbfb8aa3b, v3
	v_exp_f32_e32 v3, v3
	v_exp_f32_e32 v187, v187
	v_mul_f32_e32 v149, 0xbfb8aa3b, v149
	v_add_f32_e32 v4, v162, v4
	v_exp_f32_e32 v188, v149
	v_add_f32_e32 v149, v165, v190
	v_mul_f32_e32 v4, 0xbfb8aa3b, v4
	v_mul_f32_e32 v5, 0xbfb8aa3b, v5
	v_mul_f32_e32 v148, 0xbfb8aa3b, v148
	v_add_f32_e32 v3, 1.0, v3
	v_mul_f32_e32 v149, 0xbfb8aa3b, v149
	v_exp_f32_e32 v4, v4
	v_exp_f32_e32 v5, v5
	v_exp_f32_e32 v148, v148
	v_exp_f32_e32 v149, v149
	v_rcp_f32_e32 v190, v3
	v_add_f32_e32 v3, 1.0, v187
	v_rcp_f32_e32 v187, v3
	v_pk_add_f32 v[148:149], v[148:149], 1.0 op_sel_hi:[1,0]
	v_pk_add_f32 v[4:5], v[4:5], 1.0 op_sel_hi:[1,0]
	v_and_b32_e32 v193, 0xffff0000, v145
	v_pk_mul_f32 v[4:5], v[4:5], v[142:143]
	v_pk_mul_f32 v[142:143], v[148:149], v[186:187]
	v_add_f32_e32 v3, v157, v193
	v_pk_mul_f32 v[52:53], v[52:53], v[142:143]
	v_add_f32_e32 v142, v153, v189
	v_mul_f32_e32 v142, 0xbfb8aa3b, v142
	v_mul_f32_e32 v3, 0xbfb8aa3b, v3
	v_exp_f32_e32 v142, v142
	v_exp_f32_e32 v189, v3
	v_pk_mul_f32 v[50:51], v[50:51], v[4:5]
	v_add_f32_e32 v3, 1.0, v142
	v_pk_add_f32 v[4:5], v[188:189], 1.0 op_sel_hi:[1,0]
	global_load_dwordx4 v[186:189], v[218:219], off offset:256
	v_add_f32_e32 v145, v155, v191
	v_rcp_f32_e32 v191, v3
	s_waitcnt vmcnt(2)
; __device__ __forceinline__ void unpack8(const u32x4 w, float (&v)[8]) { v[0] = bf_lo(w.x); v[1] = bf_hi(w.x); v[2] = bf_lo(w.y); v[3] = bf_hi(w.y); v[4] = bf_lo(w.z); v[5] = bf_hi(w.z); v[6] = bf_lo(w.w); v[7] = bf_hi(w.w); }
;     __device__ __forceinline__ void after(int te, f32x4 (&acc)[2][2][4][2], const Unit& u, int wr, int wc, int fr, int fq) const {
;     ...
;                     for (int m = 0; m < 4; ++m) { const size_t r = (size_t)(row0 + ai * HALF + m * 16); gs[m] = *(const u32x4*)(proj + r * LDP + PGS + c); ga[m] = *(const u32x4*)(proj + r * LDP + PGA + c); }
; #pragma unroll
;                     for (int m = 0; m < 4; ++m) { float vs[8], va[8]; unpack8(gs[m], vs); unpack8(ga[m], va);
; #pragma unroll
;                         for (int e = 0; e < 4; ++e) {
;                             acc[ai][bj][m][0][e] *= (1.f + __expf(-(va[e] + a0[e]))) * __builtin_amdgcn_rcpf(1.f + __expf(-(vs[e] + s0[e])));
;                             acc[ai][bj][m][1][e] *= (1.f + __expf(-(va[4 + e] + a1[e]))) * __builtin_amdgcn_rcpf(1.f + __expf(-(vs[4 + e] + s1[e]))); } }
	v_lshlrev_b32_e32 v3, 16, v130
	v_mul_f32_e32 v145, 0xbfb8aa3b, v145
	v_add_f32_e32 v3, v158, v3
	v_exp_f32_e32 v145, v145
	v_mul_f32_e32 v3, 0xbfb8aa3b, v3
	v_exp_f32_e32 v3, v3
	v_pk_mul_f32 v[4:5], v[4:5], v[190:191]
	v_pk_add_f32 v[142:143], v[144:145], 1.0 op_sel_hi:[1,0]
	v_pk_mul_f32 v[48:49], v[48:49], v[4:5]
	v_pk_mul_f32 v[142:143], v[142:143], v[146:147]
	v_and_b32_e32 v5, 0xffff0000, v130
	v_lshlrev_b32_e32 v130, 16, v132
	v_add_f32_e32 v3, 1.0, v3
	v_pk_mul_f32 v[46:47], v[46:47], v[142:143]
	v_lshlrev_b32_e32 v142, 16, v131
	v_and_b32_e32 v143, 0xffff0000, v131
	v_and_b32_e32 v131, 0xffff0000, v132
	s_waitcnt vmcnt(1)
	v_lshlrev_b32_e32 v4, 16, v126
	v_and_b32_e32 v132, 0xffff0000, v126
	v_rcp_f32_e32 v126, v3
	v_add_f32_e32 v3, v150, v130
	v_mul_f32_e32 v3, 0xbfb8aa3b, v3
	v_exp_f32_e32 v3, v3
	global_load_dwordx4 v[190:193], v[216:217], off offset:256
	v_lshlrev_b32_e32 v144, 16, v133
	v_and_b32_e32 v145, 0xffff0000, v133
	v_add_f32_e32 v3, 1.0, v3
	v_rcp_f32_e32 v130, v3
	v_add_f32_e32 v3, v159, v5
	v_mul_f32_e32 v3, 0xbfb8aa3b, v3
	v_exp_f32_e32 v3, v3
	v_lshlrev_b32_e32 v133, 16, v127
	v_and_b32_e32 v146, 0xffff0000, v127
	v_lshlrev_b32_e32 v127, 16, v128
	v_add_f32_e32 v127, v154, v127
	v_mul_f32_e32 v127, 0xbfb8aa3b, v127
	v_add_f32_e32 v3, 1.0, v3
	v_and_b32_e32 v147, 0xffff0000, v128
	v_exp_f32_e32 v128, v127
	v_rcp_f32_e32 v127, v3
	v_add_f32_e32 v3, v151, v131
	v_mul_f32_e32 v3, 0xbfb8aa3b, v3
	v_exp_f32_e32 v3, v3
	v_add_f32_e32 v143, v161, v143
	v_lshlrev_b32_e32 v148, 16, v129
	v_mul_f32_e32 v143, 0xbfb8aa3b, v143
	v_add_f32_e32 v3, 1.0, v3
	v_rcp_f32_e32 v131, v3
	v_add_f32_e32 v3, v160, v142
	v_mul_f32_e32 v3, 0xbfb8aa3b, v3
	v_exp_f32_e32 v3, v3
	v_add_f32_e32 v5, v163, v132
	v_add_f32_e32 v132, v164, v133
	v_add_f32_e32 v133, v156, v148
	v_add_f32_e32 v3, 1.0, v3
	v_rcp_f32_e32 v142, v3
	v_add_f32_e32 v3, v152, v144
	v_mul_f32_e32 v3, 0xbfb8aa3b, v3
	v_exp_f32_e32 v3, v3
	v_exp_f32_e32 v143, v143
	v_mul_f32_e32 v133, 0xbfb8aa3b, v133
	v_add_f32_e32 v4, v162, v4
	v_exp_f32_e32 v144, v133
	v_add_f32_e32 v133, v165, v146
	v_mul_f32_e32 v4, 0xbfb8aa3b, v4
	v_mul_f32_e32 v5, 0xbfb8aa3b, v5
	v_mul_f32_e32 v132, 0xbfb8aa3b, v132
	v_add_f32_e32 v3, 1.0, v3
	v_mul_f32_e32 v133, 0xbfb8aa3b, v133
	v_exp_f32_e32 v4, v4
	v_exp_f32_e32 v5, v5
	v_exp_f32_e32 v132, v132
	v_exp_f32_e32 v133, v133
	v_rcp_f32_e32 v146, v3
	v_add_f32_e32 v3, 1.0, v143
	v_rcp_f32_e32 v143, v3
	v_pk_add_f32 v[132:133], v[132:133], 1.0 op_sel_hi:[1,0]
	v_pk_add_f32 v[4:5], v[4:5], 1.0 op_sel_hi:[1,0]
	v_and_b32_e32 v149, 0xffff0000, v129
	v_pk_mul_f32 v[4:5], v[4:5], v[126:127]
	v_pk_mul_f32 v[126:127], v[132:133], v[142:143]
	v_add_f32_e32 v129, v155, v147
	v_pk_mul_f32 v[44:45], v[44:45], v[126:127]
	v_add_f32_e32 v126, v153, v145
	v_mul_f32_e32 v126, 0xbfb8aa3b, v126
	v_exp_f32_e32 v126, v126
	v_mul_f32_e32 v129, 0xbfb8aa3b, v129
	v_add_f32_e32 v3, v157, v149
	v_exp_f32_e32 v129, v129
	v_mul_f32_e32 v3, 0xbfb8aa3b, v3
	v_exp_f32_e32 v145, v3
	v_add_f32_e32 v3, 1.0, v126
	v_rcp_f32_e32 v147, v3
	v_pk_add_f32 v[126:127], v[128:129], 1.0 op_sel_hi:[1,0]
	v_pk_mul_f32 v[42:43], v[42:43], v[4:5]
	v_pk_add_f32 v[4:5], v[144:145], 1.0 op_sel_hi:[1,0]
	v_pk_mul_f32 v[126:127], v[126:127], v[130:131]
	v_pk_mul_f32 v[4:5], v[4:5], v[146:147]
	v_pk_mul_f32 v[38:39], v[38:39], v[126:127]
	global_load_dwordx4 v[194:197], v[204:205], off offset:256
	global_load_dwordx4 v[198:201], v[206:207], off offset:256
	global_load_dwordx4 v[146:149], v[208:209], off offset:256
	global_load_dwordx4 v[142:145], v[210:211], off offset:256
	global_load_dwordx4 v[130:133], v[212:213], off offset:256
	global_load_dwordx4 v[126:129], v[214:215], off offset:256
	s_waitcnt vmcnt(7)
	v_lshlrev_b32_e32 v3, 16, v186
	v_add_f32_e32 v3, v158, v3
	v_mul_f32_e32 v3, 0xbfb8aa3b, v3
	v_exp_f32_e32 v3, v3
	v_lshlrev_b32_e32 v202, 16, v187
	v_and_b32_e32 v203, 0xffff0000, v187
	v_lshlrev_b32_e32 v187, 16, v188
	v_add_f32_e32 v3, 1.0, v3
	v_pk_mul_f32 v[40:41], v[40:41], v[4:5]
	v_and_b32_e32 v5, 0xffff0000, v186
	v_rcp_f32_e32 v186, v3
	v_add_f32_e32 v3, v150, v187
	v_mul_f32_e32 v3, 0xbfb8aa3b, v3
	v_exp_f32_e32 v3, v3
	v_lshlrev_b32_e32 v205, 16, v189
	v_and_b32_e32 v207, 0xffff0000, v189
	s_waitcnt vmcnt(6)
	v_lshlrev_b32_e32 v4, 16, v190
	v_add_f32_e32 v3, 1.0, v3
	v_and_b32_e32 v189, 0xffff0000, v190
	v_rcp_f32_e32 v190, v3
	v_add_f32_e32 v3, v159, v5
	v_mul_f32_e32 v3, 0xbfb8aa3b, v3
	v_exp_f32_e32 v3, v3
	v_and_b32_e32 v204, 0xffff0000, v188
	v_lshlrev_b32_e32 v188, 16, v192
	v_add_f32_e32 v187, v154, v188
	v_mul_f32_e32 v187, 0xbfb8aa3b, v187
	v_add_f32_e32 v3, 1.0, v3
	v_exp_f32_e32 v188, v187
	v_rcp_f32_e32 v187, v3
	v_add_f32_e32 v3, v151, v204
	v_mul_f32_e32 v3, 0xbfb8aa3b, v3
	v_exp_f32_e32 v3, v3
	v_lshlrev_b32_e32 v206, 16, v191
	v_and_b32_e32 v208, 0xffff0000, v191
	v_and_b32_e32 v191, 0xffff0000, v192
	v_add_f32_e32 v3, 1.0, v3
	v_add_f32_e32 v5, v163, v189
	v_add_f32_e32 v189, v155, v191
	v_rcp_f32_e32 v191, v3
	v_add_f32_e32 v3, v160, v202
	v_mul_f32_e32 v3, 0xbfb8aa3b, v3
	v_exp_f32_e32 v3, v3
	v_add_f32_e32 v203, v161, v203
	v_lshlrev_b32_e32 v209, 16, v193
	v_mul_f32_e32 v203, 0xbfb8aa3b, v203
	v_add_f32_e32 v3, 1.0, v3
	v_rcp_f32_e32 v202, v3
	v_add_f32_e32 v3, v152, v205
	v_mul_f32_e32 v3, 0xbfb8aa3b, v3
	v_exp_f32_e32 v3, v3
	v_and_b32_e32 v210, 0xffff0000, v193
	v_add_f32_e32 v193, v156, v209
	v_exp_f32_e32 v203, v203
	v_mul_f32_e32 v193, 0xbfb8aa3b, v193
	v_add_f32_e32 v4, v162, v4
	v_add_f32_e32 v192, v164, v206
	v_exp_f32_e32 v204, v193
	v_add_f32_e32 v193, v165, v208
	v_mul_f32_e32 v4, 0xbfb8aa3b, v4
	v_mul_f32_e32 v5, 0xbfb8aa3b, v5
	v_mul_f32_e32 v192, 0xbfb8aa3b, v192
	v_add_f32_e32 v3, 1.0, v3
	v_mul_f32_e32 v193, 0xbfb8aa3b, v193
	v_exp_f32_e32 v4, v4
	v_exp_f32_e32 v5, v5
	v_exp_f32_e32 v192, v192
	v_exp_f32_e32 v193, v193
	v_rcp_f32_e32 v206, v3
	v_add_f32_e32 v3, 1.0, v203
	v_rcp_f32_e32 v203, v3
	v_pk_add_f32 v[192:193], v[192:193], 1.0 op_sel_hi:[1,0]
	v_pk_add_f32 v[4:5], v[4:5], 1.0 op_sel_hi:[1,0]
	v_add_f32_e32 v3, v157, v210
	v_pk_mul_f32 v[4:5], v[4:5], v[186:187]
	v_pk_mul_f32 v[186:187], v[192:193], v[202:203]
	v_mul_f32_e32 v3, 0xbfb8aa3b, v3
	v_pk_mul_f32 v[36:37], v[36:37], v[186:187]
	v_add_f32_e32 v186, v153, v207
	v_mul_f32_e32 v186, 0xbfb8aa3b, v186
	v_exp_f32_e32 v186, v186
	v_exp_f32_e32 v205, v3
	v_mul_f32_e32 v189, 0xbfb8aa3b, v189
	v_exp_f32_e32 v189, v189
	v_add_f32_e32 v3, 1.0, v186
	v_rcp_f32_e32 v207, v3
	s_waitcnt vmcnt(5)
; __device__ __forceinline__ void unpack8(const u32x4 w, float (&v)[8]) { v[0] = bf_lo(w.x); v[1] = bf_hi(w.x); v[2] = bf_lo(w.y); v[3] = bf_hi(w.y); v[4] = bf_lo(w.z); v[5] = bf_hi(w.z); v[6] = bf_lo(w.w); v[7] = bf_hi(w.w); }
;     __device__ __forceinline__ void after(int te, f32x4 (&acc)[2][2][4][2], const Unit& u, int wr, int wc, int fr, int fq) const {
;     ...
;                     for (int m = 0; m < 4; ++m) { float vs[8], va[8]; unpack8(gs[m], vs); unpack8(ga[m], va);
; #pragma unroll
;                         for (int e = 0; e < 4; ++e) {
;                             acc[ai][bj][m][0][e] *= (1.f + __expf(-(va[e] + a0[e]))) * __builtin_amdgcn_rcpf(1.f + __expf(-(vs[e] + s0[e])));
;                             acc[ai][bj][m][1][e] *= (1.f + __expf(-(va[4 + e] + a1[e]))) * __builtin_amdgcn_rcpf(1.f + __expf(-(vs[4 + e] + s1[e]))); } }
	v_lshlrev_b32_e32 v3, 16, v194
	v_add_f32_e32 v3, v158, v3
	v_mul_f32_e32 v3, 0xbfb8aa3b, v3
	v_exp_f32_e32 v3, v3
	v_pk_add_f32 v[186:187], v[188:189], 1.0 op_sel_hi:[1,0]
	v_pk_mul_f32 v[34:35], v[34:35], v[4:5]
	v_pk_mul_f32 v[186:187], v[186:187], v[190:191]
	v_add_f32_e32 v3, 1.0, v3
	v_pk_mul_f32 v[30:31], v[30:31], v[186:187]
	v_lshlrev_b32_e32 v187, 16, v196
	v_rcp_f32_e32 v186, v3
	v_add_f32_e32 v3, v150, v187
	v_mul_f32_e32 v3, 0xbfb8aa3b, v3
	v_exp_f32_e32 v3, v3
	v_pk_add_f32 v[4:5], v[204:205], 1.0 op_sel_hi:[1,0]
	s_waitcnt vmcnt(4)
	v_lshlrev_b32_e32 v188, 16, v200
	v_pk_mul_f32 v[4:5], v[4:5], v[206:207]
	v_add_f32_e32 v3, 1.0, v3
	v_pk_mul_f32 v[32:33], v[32:33], v[4:5]
	v_and_b32_e32 v5, 0xffff0000, v194
	v_rcp_f32_e32 v190, v3
	v_add_f32_e32 v3, v159, v5
	v_mul_f32_e32 v3, 0xbfb8aa3b, v3
	v_exp_f32_e32 v3, v3
	v_add_f32_e32 v187, v154, v188
	v_and_b32_e32 v189, 0xffff0000, v196
	v_mul_f32_e32 v187, 0xbfb8aa3b, v187
	v_add_f32_e32 v3, 1.0, v3
	v_exp_f32_e32 v188, v187
	v_rcp_f32_e32 v187, v3
	v_add_f32_e32 v3, v151, v189
	v_mul_f32_e32 v3, 0xbfb8aa3b, v3
	v_exp_f32_e32 v3, v3
	v_lshlrev_b32_e32 v192, 16, v195
	v_and_b32_e32 v191, 0xffff0000, v198
	v_add_f32_e32 v5, v163, v191
	v_add_f32_e32 v3, 1.0, v3
	v_rcp_f32_e32 v191, v3
	v_add_f32_e32 v3, v160, v192
	v_mul_f32_e32 v3, 0xbfb8aa3b, v3
	v_exp_f32_e32 v3, v3
	v_and_b32_e32 v193, 0xffff0000, v195
	v_lshlrev_b32_e32 v195, 16, v197
	v_lshlrev_b32_e32 v194, 16, v199
	v_add_f32_e32 v3, 1.0, v3
	v_add_f32_e32 v192, v164, v194
	v_rcp_f32_e32 v194, v3
	v_add_f32_e32 v3, v152, v195
	v_mul_f32_e32 v3, 0xbfb8aa3b, v3
	v_add_f32_e32 v193, v161, v193
	v_lshlrev_b32_e32 v4, 16, v198
	v_and_b32_e32 v198, 0xffff0000, v199
	v_lshlrev_b32_e32 v199, 16, v201
	v_exp_f32_e32 v3, v3
	v_mul_f32_e32 v193, 0xbfb8aa3b, v193
	v_add_f32_e32 v195, v156, v199
	v_exp_f32_e32 v199, v193
	v_and_b32_e32 v196, 0xffff0000, v200
	v_mul_f32_e32 v195, 0xbfb8aa3b, v195
	v_add_f32_e32 v4, v162, v4
	v_add_f32_e32 v189, v155, v196
	v_exp_f32_e32 v196, v195
	v_add_f32_e32 v195, v165, v198
	v_mul_f32_e32 v4, 0xbfb8aa3b, v4
	v_mul_f32_e32 v5, 0xbfb8aa3b, v5
	v_mul_f32_e32 v192, 0xbfb8aa3b, v192
	v_add_f32_e32 v3, 1.0, v3
	v_mul_f32_e32 v193, 0xbfb8aa3b, v195
	v_exp_f32_e32 v4, v4
	v_exp_f32_e32 v5, v5
	v_exp_f32_e32 v192, v192
	v_exp_f32_e32 v193, v193
	v_rcp_f32_e32 v198, v3
	v_add_f32_e32 v3, 1.0, v199
	v_rcp_f32_e32 v195, v3
	v_pk_add_f32 v[192:193], v[192:193], 1.0 op_sel_hi:[1,0]
	v_pk_add_f32 v[4:5], v[4:5], 1.0 op_sel_hi:[1,0]
	v_and_b32_e32 v197, 0xffff0000, v197
	v_pk_mul_f32 v[4:5], v[4:5], v[186:187]
	v_pk_mul_f32 v[186:187], v[192:193], v[194:195]
	v_and_b32_e32 v200, 0xffff0000, v201
	v_pk_mul_f32 v[28:29], v[28:29], v[186:187]
	v_add_f32_e32 v186, v153, v197
	v_mul_f32_e32 v186, 0xbfb8aa3b, v186
	v_exp_f32_e32 v186, v186
	v_add_f32_e32 v3, v157, v200
	v_mul_f32_e32 v3, 0xbfb8aa3b, v3
	v_exp_f32_e32 v197, v3
	v_add_f32_e32 v3, 1.0, v186
	v_rcp_f32_e32 v199, v3
	s_waitcnt vmcnt(3)
	v_lshlrev_b32_e32 v3, 16, v146
	v_mul_f32_e32 v189, 0xbfb8aa3b, v189
	v_add_f32_e32 v3, v158, v3
	v_exp_f32_e32 v189, v189
	v_mul_f32_e32 v3, 0xbfb8aa3b, v3
	v_exp_f32_e32 v3, v3
	v_pk_mul_f32 v[26:27], v[26:27], v[4:5]
	v_pk_add_f32 v[4:5], v[196:197], 1.0 op_sel_hi:[1,0]
	v_pk_add_f32 v[186:187], v[188:189], 1.0 op_sel_hi:[1,0]
	v_pk_mul_f32 v[4:5], v[4:5], v[198:199]
	v_pk_mul_f32 v[186:187], v[186:187], v[190:191]
	v_pk_mul_f32 v[24:25], v[24:25], v[4:5]
	v_and_b32_e32 v5, 0xffff0000, v146
	v_lshlrev_b32_e32 v146, 16, v148
	v_add_f32_e32 v3, 1.0, v3
	v_pk_mul_f32 v[22:23], v[22:23], v[186:187]
	v_lshlrev_b32_e32 v186, 16, v147
	v_and_b32_e32 v187, 0xffff0000, v147
	v_and_b32_e32 v147, 0xffff0000, v148
	s_waitcnt vmcnt(2)
; __device__ __forceinline__ void unpack8(const u32x4 w, float (&v)[8]) { v[0] = bf_lo(w.x); v[1] = bf_hi(w.x); v[2] = bf_lo(w.y); v[3] = bf_hi(w.y); v[4] = bf_lo(w.z); v[5] = bf_hi(w.z); v[6] = bf_lo(w.w); v[7] = bf_hi(w.w); }
;     __device__ __forceinline__ void after(int te, f32x4 (&acc)[2][2][4][2], const Unit& u, int wr, int wc, int fr, int fq) const {
;     ...
;                     for (int m = 0; m < 4; ++m) { float vs[8], va[8]; unpack8(gs[m], vs); unpack8(ga[m], va);
; #pragma unroll
;                         for (int e = 0; e < 4; ++e) {
;                             acc[ai][bj][m][0][e] *= (1.f + __expf(-(va[e] + a0[e]))) * __builtin_amdgcn_rcpf(1.f + __expf(-(vs[e] + s0[e])));
;                             acc[ai][bj][m][1][e] *= (1.f + __expf(-(va[4 + e] + a1[e]))) * __builtin_amdgcn_rcpf(1.f + __expf(-(vs[4 + e] + s1[e]))); } }
	v_lshlrev_b32_e32 v4, 16, v142
	v_and_b32_e32 v148, 0xffff0000, v142
	v_rcp_f32_e32 v142, v3
	v_add_f32_e32 v3, v150, v146
	v_mul_f32_e32 v3, 0xbfb8aa3b, v3
	v_exp_f32_e32 v3, v3
	v_lshlrev_b32_e32 v188, 16, v149
	v_and_b32_e32 v189, 0xffff0000, v149
	v_lshlrev_b32_e32 v149, 16, v143
	v_add_f32_e32 v3, 1.0, v3
	v_rcp_f32_e32 v146, v3
	v_add_f32_e32 v3, v159, v5
	v_mul_f32_e32 v3, 0xbfb8aa3b, v3
	v_exp_f32_e32 v3, v3
	v_and_b32_e32 v190, 0xffff0000, v143
	v_lshlrev_b32_e32 v143, 16, v144
	v_add_f32_e32 v143, v154, v143
	v_mul_f32_e32 v143, 0xbfb8aa3b, v143
	v_add_f32_e32 v3, 1.0, v3
	v_and_b32_e32 v191, 0xffff0000, v144
	v_exp_f32_e32 v144, v143
	v_rcp_f32_e32 v143, v3
	v_add_f32_e32 v3, v151, v147
	v_mul_f32_e32 v3, 0xbfb8aa3b, v3
	v_exp_f32_e32 v3, v3
	v_add_f32_e32 v187, v161, v187
	v_lshlrev_b32_e32 v192, 16, v145
	v_mul_f32_e32 v187, 0xbfb8aa3b, v187
	v_add_f32_e32 v3, 1.0, v3
	v_rcp_f32_e32 v147, v3
	v_add_f32_e32 v3, v160, v186
	v_mul_f32_e32 v3, 0xbfb8aa3b, v3
	v_exp_f32_e32 v3, v3
	v_add_f32_e32 v5, v163, v148
	v_add_f32_e32 v148, v164, v149
	v_add_f32_e32 v149, v156, v192
	v_add_f32_e32 v3, 1.0, v3
	v_rcp_f32_e32 v186, v3
	v_add_f32_e32 v3, v152, v188
	v_mul_f32_e32 v3, 0xbfb8aa3b, v3
	v_exp_f32_e32 v3, v3
	v_exp_f32_e32 v187, v187
	v_mul_f32_e32 v149, 0xbfb8aa3b, v149
	v_add_f32_e32 v4, v162, v4
	v_exp_f32_e32 v188, v149
	v_add_f32_e32 v149, v165, v190
	v_mul_f32_e32 v4, 0xbfb8aa3b, v4
	v_mul_f32_e32 v5, 0xbfb8aa3b, v5
	v_mul_f32_e32 v148, 0xbfb8aa3b, v148
	v_add_f32_e32 v3, 1.0, v3
	v_mul_f32_e32 v149, 0xbfb8aa3b, v149
	v_exp_f32_e32 v4, v4
	v_exp_f32_e32 v5, v5
	v_exp_f32_e32 v148, v148
	v_exp_f32_e32 v149, v149
	v_rcp_f32_e32 v190, v3
	v_add_f32_e32 v3, 1.0, v187
	v_rcp_f32_e32 v187, v3
	v_pk_add_f32 v[148:149], v[148:149], 1.0 op_sel_hi:[1,0]
	v_pk_add_f32 v[4:5], v[4:5], 1.0 op_sel_hi:[1,0]
	v_and_b32_e32 v193, 0xffff0000, v145
	v_pk_mul_f32 v[4:5], v[4:5], v[142:143]
	v_pk_mul_f32 v[142:143], v[148:149], v[186:187]
	v_add_f32_e32 v3, v157, v193
	v_pk_mul_f32 v[20:21], v[20:21], v[142:143]
	v_add_f32_e32 v142, v153, v189
	v_mul_f32_e32 v142, 0xbfb8aa3b, v142
	v_exp_f32_e32 v142, v142
	v_mul_f32_e32 v3, 0xbfb8aa3b, v3
	v_exp_f32_e32 v189, v3
	v_add_f32_e32 v145, v155, v191
	v_add_f32_e32 v3, 1.0, v142
	v_rcp_f32_e32 v191, v3
	s_waitcnt vmcnt(1)
	v_lshlrev_b32_e32 v3, 16, v130
	v_mul_f32_e32 v145, 0xbfb8aa3b, v145
	v_add_f32_e32 v3, v158, v3
	v_exp_f32_e32 v145, v145
	v_mul_f32_e32 v3, 0xbfb8aa3b, v3
	v_exp_f32_e32 v3, v3
	v_pk_mul_f32 v[18:19], v[18:19], v[4:5]
	v_pk_add_f32 v[4:5], v[188:189], 1.0 op_sel_hi:[1,0]
	v_pk_add_f32 v[142:143], v[144:145], 1.0 op_sel_hi:[1,0]
	v_pk_mul_f32 v[4:5], v[4:5], v[190:191]
	v_pk_mul_f32 v[142:143], v[142:143], v[146:147]
	v_pk_mul_f32 v[16:17], v[16:17], v[4:5]
	v_and_b32_e32 v5, 0xffff0000, v130
	v_lshlrev_b32_e32 v130, 16, v132
	v_add_f32_e32 v3, 1.0, v3
	v_pk_mul_f32 v[14:15], v[14:15], v[142:143]
	v_lshlrev_b32_e32 v142, 16, v131
	v_and_b32_e32 v143, 0xffff0000, v131
	v_and_b32_e32 v131, 0xffff0000, v132
	s_waitcnt vmcnt(0)
	v_lshlrev_b32_e32 v4, 16, v126
	v_and_b32_e32 v132, 0xffff0000, v126
	v_rcp_f32_e32 v126, v3
	v_add_f32_e32 v3, v150, v130
	v_mul_f32_e32 v3, 0xbfb8aa3b, v3
	v_exp_f32_e32 v3, v3
	v_lshlrev_b32_e32 v144, 16, v133
	v_and_b32_e32 v145, 0xffff0000, v133
	v_lshlrev_b32_e32 v133, 16, v127
	v_add_f32_e32 v3, 1.0, v3
	v_rcp_f32_e32 v130, v3
	v_add_f32_e32 v3, v159, v5
	v_mul_f32_e32 v3, 0xbfb8aa3b, v3
	v_exp_f32_e32 v3, v3
	v_and_b32_e32 v146, 0xffff0000, v127
	v_lshlrev_b32_e32 v127, 16, v128
	v_add_f32_e32 v127, v154, v127
	v_mul_f32_e32 v127, 0xbfb8aa3b, v127
	v_add_f32_e32 v3, 1.0, v3
	v_and_b32_e32 v147, 0xffff0000, v128
	v_exp_f32_e32 v128, v127
	v_rcp_f32_e32 v127, v3
	v_add_f32_e32 v3, v151, v131
	v_mul_f32_e32 v3, 0xbfb8aa3b, v3
	v_exp_f32_e32 v3, v3
	v_add_f32_e32 v143, v161, v143
	v_lshlrev_b32_e32 v148, 16, v129
	v_mul_f32_e32 v143, 0xbfb8aa3b, v143
	v_add_f32_e32 v3, 1.0, v3
	v_rcp_f32_e32 v131, v3
	v_add_f32_e32 v3, v160, v142
	v_mul_f32_e32 v3, 0xbfb8aa3b, v3
	v_exp_f32_e32 v3, v3
	v_add_f32_e32 v5, v163, v132
	v_add_f32_e32 v132, v164, v133
	v_add_f32_e32 v133, v156, v148
	v_add_f32_e32 v3, 1.0, v3
	v_rcp_f32_e32 v142, v3
	v_add_f32_e32 v3, v152, v144
	v_mul_f32_e32 v3, 0xbfb8aa3b, v3
	v_exp_f32_e32 v3, v3
	v_exp_f32_e32 v143, v143
	v_mul_f32_e32 v133, 0xbfb8aa3b, v133
	v_add_f32_e32 v4, v162, v4
	v_exp_f32_e32 v144, v133
	v_add_f32_e32 v133, v165, v146
	v_mul_f32_e32 v4, 0xbfb8aa3b, v4
	v_mul_f32_e32 v5, 0xbfb8aa3b, v5
	v_mul_f32_e32 v132, 0xbfb8aa3b, v132
	v_add_f32_e32 v3, 1.0, v3
	v_mul_f32_e32 v133, 0xbfb8aa3b, v133
	v_exp_f32_e32 v4, v4
	v_exp_f32_e32 v5, v5
	v_exp_f32_e32 v132, v132
	v_exp_f32_e32 v133, v133
	v_rcp_f32_e32 v146, v3
	v_add_f32_e32 v3, 1.0, v143
	v_rcp_f32_e32 v143, v3
	v_pk_add_f32 v[132:133], v[132:133], 1.0 op_sel_hi:[1,0]
	v_pk_add_f32 v[4:5], v[4:5], 1.0 op_sel_hi:[1,0]
	v_and_b32_e32 v149, 0xffff0000, v129
	v_pk_mul_f32 v[4:5], v[4:5], v[126:127]
	v_pk_mul_f32 v[126:127], v[132:133], v[142:143]
	v_add_f32_e32 v129, v155, v147
	v_pk_mul_f32 v[12:13], v[12:13], v[126:127]
	v_add_f32_e32 v126, v153, v145
	v_mul_f32_e32 v126, 0xbfb8aa3b, v126
	v_exp_f32_e32 v126, v126
	v_add_f32_e32 v3, v157, v149
	v_mul_f32_e32 v129, 0xbfb8aa3b, v129
	v_mul_f32_e32 v3, 0xbfb8aa3b, v3
	v_exp_f32_e32 v129, v129
	v_exp_f32_e32 v145, v3
	v_add_f32_e32 v3, 1.0, v126
	v_rcp_f32_e32 v147, v3
	v_pk_mul_f32 v[10:11], v[10:11], v[4:5]
	v_pk_add_f32 v[4:5], v[144:145], 1.0 op_sel_hi:[1,0]
	v_pk_add_f32 v[126:127], v[128:129], 1.0 op_sel_hi:[1,0]
	v_pk_mul_f32 v[4:5], v[4:5], v[146:147]
	v_pk_mul_f32 v[126:127], v[126:127], v[130:131]
	v_pk_mul_f32 v[8:9], v[8:9], v[4:5]
	v_pk_mul_f32 v[6:7], v[6:7], v[126:127]
